# extra s_setprio 0/1 flips after every 8th MFMA of each 16-MFMA run in GEMM loops
# baseline (speedup 1.0000x reference)
; #define PG8_STAGE(bufoff, gbase, voff) do { _Pragma("unroll") for (int _i = 0; _i < 2; ++_i) \
;         __builtin_amdgcn_global_load_lds((const unsigned*)((const char*)(gbase) + (voff)[_i]), (PG8_LAS unsigned*)(lds + (bufoff) + ldsw + _i * 8192), 16, 0, 0); } while (0)
; #define PG8_LDA(dst, b, h) do { _Pragma("unroll") for (int m = 0; m < 4; ++m) _Pragma("unroll") for (int k = 0; k < 2; ++k) dst[m][k] = *(const PG8_LAS bf16x8*)(lds + PG8_SA(b, h) + aoff + m * 2048 + k * 1024); } while (0)
; #define PG8_LDB(dst, b, h) do { _Pragma("unroll") for (int n = 0; n < 2; ++n) _Pragma("unroll") for (int k = 0; k < 2; ++k) dst[n][k] = *(const PG8_LAS bf16x8*)(lds + PG8_SB(b, h) + boff + n * 2048 + k * 1024); } while (0)
; #define PG8_MMA(ai, bj, At, Bt) do { __builtin_amdgcn_s_setprio(1); _Pragma("unroll") for (int m = 0; m < 4; ++m) _Pragma("unroll") for (int n = 0; n < 2; ++n) _Pragma("unroll") for (int k = 0; k < 2; ++k) \
;         acc[ai][bj][m][n] = __builtin_amdgcn_mfma_f32_16x16x32_bf16(Bt[n][k], At[m][k], acc[ai][bj][m][n], 0, 0, 0); __builtin_amdgcn_s_setprio(0); } while (0)
; #define PG8_WAIT_V(n) asm volatile("s_waitcnt vmcnt(" #n ")" ::: "memory")
; #define PG8_WAIT_L(n) asm volatile("s_waitcnt lgkmcnt(" #n ")" ::: "memory")
; #define PG8_BAR __builtin_amdgcn_s_barrier()
; #define PG8_SCHED __builtin_amdgcn_sched_barrier(0)
; template <class Epi, class Sched, bool ALIGN_EPI = false, bool SP2 = false>
; __device__ __forceinline__ void gemm_phase(PG8_LAS unsigned char* lds, const Gemm g, const Sched& S, const Epi& E) {
;     ...
;             PG8_LDB(B0, 0, 0); PG8_LDB(B1, 0, 1); PG8_SCHED; PG8_LDA(At, 0, 0); PG8_STAGE(PG8_SA(1, 1), a1 + hstep, voffA);
;             PG8_WAIT_V(8); PG8_WAIT_L(0); PG8_BAR; PG8_MMA(0, 0, At, B0); PG8_MMA(0, 1, At, B1); PG8_BAR; PG8_SCHED;
;             PG8_LDA(At, 0, 1); PG8_STAGE(PG8_SB(0, 0), b2, voffB); PG8_STAGE(PG8_SB(0, 1), b2 + hstep, voffB); PG8_STAGE(PG8_SA(0, 0), a2, voffA);
;             PG8_WAIT_V(8); PG8_WAIT_L(0); PG8_BAR; PG8_MMA(1, 0, At, B0); PG8_MMA(1, 1, At, B1); PG8_BAR; PG8_SCHED;
.LBB0_35:
	s_add_u32 s24, s0, 0xfffc0080
	s_addc_u32 s25, s1, -1
	s_add_i32 s52, 0, 0x10000
	s_cmp_eq_u32 s51, 12
	s_cselect_b32 s27, s4, s25
	s_cselect_b32 s26, s5, s24
	s_cselect_b32 s25, s3, s50
	s_cselect_b32 s24, s19, s49
	s_add_i32 s54, 0, 0x14000
	v_add_u32_e32 v156, s52, v141
	v_add_u32_e32 v172, s54, v141
	ds_read_b128 v[144:147], v156
	ds_read_b128 v[148:151], v156 offset:1024
	ds_read_b128 v[152:155], v156 offset:2048
	ds_read_b128 v[156:159], v156 offset:3072
	ds_read_b128 v[160:163], v172
	ds_read_b128 v[164:167], v172 offset:1024
	ds_read_b128 v[168:171], v172 offset:2048
	ds_read_b128 v[172:175], v172 offset:3072
	v_lshl_add_u64 v[214:215], s[0:1], 0, v[136:137]
	s_add_i32 m0, s40, 0xc000
	ds_read_b128 v[176:179], v143
	ds_read_b128 v[180:183], v143 offset:1024
	ds_read_b128 v[194:197], v143 offset:2048
	ds_read_b128 v[198:201], v143 offset:3072
	ds_read_b128 v[202:205], v143 offset:4096
	ds_read_b128 v[206:209], v143 offset:5120
	ds_read_b128 v[210:213], v143 offset:6144
	ds_read_b128 v[228:231], v143 offset:7168
	global_load_lds_dwordx4 v[214:215], off
	v_lshl_add_u64 v[214:215], s[0:1], 0, v[138:139]
	s_add_i32 m0, s40, 0xe000
	s_nop 0
	global_load_lds_dwordx4 v[214:215], off
	s_waitcnt vmcnt(8)
	s_waitcnt lgkmcnt(0)
	s_barrier
	s_setprio 1
	s_waitcnt lgkmcnt(0)
	v_mfma_f32_16x16x32_bf16 v[124:127], v[144:147], v[176:179], v[124:127]
	v_mfma_f32_16x16x32_bf16 v[116:119], v[152:155], v[176:179], v[116:119]
	v_mfma_f32_16x16x32_bf16 v[108:111], v[144:147], v[194:197], v[108:111]
	v_mfma_f32_16x16x32_bf16 v[100:103], v[152:155], v[194:197], v[100:103]
	v_mfma_f32_16x16x32_bf16 v[92:95], v[144:147], v[202:205], v[92:95]
	v_mfma_f32_16x16x32_bf16 v[84:87], v[152:155], v[202:205], v[84:87]
	v_mfma_f32_16x16x32_bf16 v[76:79], v[144:147], v[210:213], v[76:79]
	v_mfma_f32_16x16x32_bf16 v[68:71], v[152:155], v[210:213], v[68:71]
	s_setprio 0
	s_setprio 1
	v_mfma_f32_16x16x32_bf16 v[124:127], v[148:151], v[180:183], v[124:127]
	v_mfma_f32_16x16x32_bf16 v[116:119], v[156:159], v[180:183], v[116:119]
	v_mfma_f32_16x16x32_bf16 v[108:111], v[148:151], v[198:201], v[108:111]
	v_mfma_f32_16x16x32_bf16 v[100:103], v[156:159], v[198:201], v[100:103]
	v_mfma_f32_16x16x32_bf16 v[92:95], v[148:151], v[206:209], v[92:95]
	v_mfma_f32_16x16x32_bf16 v[84:87], v[156:159], v[206:209], v[84:87]
	v_mfma_f32_16x16x32_bf16 v[76:79], v[148:151], v[228:231], v[76:79]
	v_mfma_f32_16x16x32_bf16 v[68:71], v[156:159], v[228:231], v[68:71]
	s_setprio 0
	s_setprio 1
	v_mfma_f32_16x16x32_bf16 v[120:123], v[160:163], v[176:179], v[120:123]
	v_mfma_f32_16x16x32_bf16 v[112:115], v[168:171], v[176:179], v[112:115]
	v_mfma_f32_16x16x32_bf16 v[104:107], v[160:163], v[194:197], v[104:107]
	v_mfma_f32_16x16x32_bf16 v[96:99], v[168:171], v[194:197], v[96:99]
	v_mfma_f32_16x16x32_bf16 v[88:91], v[160:163], v[202:205], v[88:91]
	v_mfma_f32_16x16x32_bf16 v[80:83], v[168:171], v[202:205], v[80:83]
	v_mfma_f32_16x16x32_bf16 v[72:75], v[160:163], v[210:213], v[72:75]
	v_mfma_f32_16x16x32_bf16 v[64:67], v[168:171], v[210:213], v[64:67]
	s_setprio 0
	s_setprio 1
	v_mfma_f32_16x16x32_bf16 v[120:123], v[164:167], v[180:183], v[120:123]
	v_mfma_f32_16x16x32_bf16 v[112:115], v[172:175], v[180:183], v[112:115]
	v_mfma_f32_16x16x32_bf16 v[104:107], v[164:167], v[198:201], v[104:107]
	v_mfma_f32_16x16x32_bf16 v[96:99], v[172:175], v[198:201], v[96:99]
	v_mfma_f32_16x16x32_bf16 v[88:91], v[164:167], v[206:209], v[88:91]
	v_mfma_f32_16x16x32_bf16 v[80:83], v[172:175], v[206:209], v[80:83]
	v_mfma_f32_16x16x32_bf16 v[72:75], v[164:167], v[228:231], v[72:75]
	v_mfma_f32_16x16x32_bf16 v[64:67], v[172:175], v[228:231], v[64:67]
	s_setprio 0
	s_barrier
	s_add_i32 s52, s52, s39
	v_lshl_add_u64 v[214:215], s[24:25], 0, v[132:133]
	s_mov_b32 m0, s52
	ds_read_b128 v[176:179], v143 offset:16384
	ds_read_b128 v[180:183], v143 offset:17408
	ds_read_b128 v[194:197], v143 offset:18432
	ds_read_b128 v[198:201], v143 offset:19456
	ds_read_b128 v[202:205], v143 offset:20480
	ds_read_b128 v[206:209], v143 offset:21504
	ds_read_b128 v[210:213], v143 offset:22528
	ds_read_b128 v[228:231], v143 offset:23552
	global_load_lds_dwordx4 v[214:215], off
	s_add_i32 m0, s52, 0x2000
	s_add_u32 s52, s24, 0x40000
	v_lshl_add_u64 v[224:225], s[24:25], 0, v[128:129]
	s_addc_u32 s53, s25, 0
	s_add_i32 s54, s54, s39
	global_load_lds_dwordx4 v[224:225], off
	v_lshl_add_u64 v[226:227], s[52:53], 0, v[132:133]
	s_mov_b32 m0, s54
	v_lshl_add_u64 v[232:233], s[26:27], 0, v[130:131]
	global_load_lds_dwordx4 v[226:227], off
	v_lshl_add_u64 v[226:227], s[52:53], 0, v[128:129]
	s_add_i32 m0, s54, 0x2000
	s_nop 0
	global_load_lds_dwordx4 v[226:227], off
	v_lshl_add_u64 v[226:227], s[26:27], 0, v[134:135]
	s_mov_b32 m0, s40
	s_nop 0
	global_load_lds_dwordx4 v[226:227], off
	s_mov_b32 m0, s41
	s_nop 0
	global_load_lds_dwordx4 v[232:233], off
	s_waitcnt vmcnt(8)
	s_waitcnt lgkmcnt(0)
	s_barrier
; #define PG8_STAGE(bufoff, gbase, voff) do { _Pragma("unroll") for (int _i = 0; _i < 2; ++_i) \
;         __builtin_amdgcn_global_load_lds((const unsigned*)((const char*)(gbase) + (voff)[_i]), (PG8_LAS unsigned*)(lds + (bufoff) + ldsw + _i * 8192), 16, 0, 0); } while (0)
; #define PG8_LDA(dst, b, h) do { _Pragma("unroll") for (int m = 0; m < 4; ++m) _Pragma("unroll") for (int k = 0; k < 2; ++k) dst[m][k] = *(const PG8_LAS bf16x8*)(lds + PG8_SA(b, h) + aoff + m * 2048 + k * 1024); } while (0)
; #define PG8_LDB(dst, b, h) do { _Pragma("unroll") for (int n = 0; n < 2; ++n) _Pragma("unroll") for (int k = 0; k < 2; ++k) dst[n][k] = *(const PG8_LAS bf16x8*)(lds + PG8_SB(b, h) + boff + n * 2048 + k * 1024); } while (0)
; #define PG8_MMA(ai, bj, At, Bt) do { __builtin_amdgcn_s_setprio(1); _Pragma("unroll") for (int m = 0; m < 4; ++m) _Pragma("unroll") for (int n = 0; n < 2; ++n) _Pragma("unroll") for (int k = 0; k < 2; ++k) \
;         acc[ai][bj][m][n] = __builtin_amdgcn_mfma_f32_16x16x32_bf16(Bt[n][k], At[m][k], acc[ai][bj][m][n], 0, 0, 0); __builtin_amdgcn_s_setprio(0); } while (0)
; #define PG8_WAIT_V(n) asm volatile("s_waitcnt vmcnt(" #n ")" ::: "memory")
; #define PG8_WAIT_L(n) asm volatile("s_waitcnt lgkmcnt(" #n ")" ::: "memory")
; #define PG8_BAR __builtin_amdgcn_s_barrier()
; #define PG8_SCHED __builtin_amdgcn_sched_barrier(0)
; template <class Epi, class Sched, bool ALIGN_EPI = false, bool SP2 = false>
; __device__ __forceinline__ void gemm_phase(PG8_LAS unsigned char* lds, const Gemm g, const Sched& S, const Epi& E) {
;     ...
;             PG8_WAIT_V(8); PG8_WAIT_L(0); PG8_BAR; PG8_MMA(1, 0, At, B0); PG8_MMA(1, 1, At, B1); PG8_BAR; PG8_SCHED;
;             PG8_LDB(B0, 1, 0); PG8_LDB(B1, 1, 1); PG8_SCHED; PG8_LDA(At, 1, 0); PG8_STAGE(PG8_SA(0, 1), a2 + hstep, voffA);
;             PG8_WAIT_V(8); PG8_WAIT_L(0); PG8_BAR; PG8_MMA(0, 0, At, B0); PG8_MMA(0, 1, At, B1); PG8_BAR; PG8_SCHED;
	s_setprio 1
	s_waitcnt lgkmcnt(0)
	v_mfma_f32_16x16x32_bf16 v[60:63], v[144:147], v[176:179], v[60:63]
	v_mfma_f32_16x16x32_bf16 v[52:55], v[152:155], v[176:179], v[52:55]
	v_mfma_f32_16x16x32_bf16 v[44:47], v[144:147], v[194:197], v[44:47]
	v_mfma_f32_16x16x32_bf16 v[36:39], v[152:155], v[194:197], v[36:39]
	v_mfma_f32_16x16x32_bf16 v[28:31], v[144:147], v[202:205], v[28:31]
	v_mfma_f32_16x16x32_bf16 v[20:23], v[152:155], v[202:205], v[20:23]
	v_mfma_f32_16x16x32_bf16 v[12:15], v[144:147], v[210:213], v[12:15]
	v_mfma_f32_16x16x32_bf16 v[4:7], v[152:155], v[210:213], v[4:7]
	s_setprio 0
	s_setprio 1
	v_mfma_f32_16x16x32_bf16 v[60:63], v[148:151], v[180:183], v[60:63]
	v_mfma_f32_16x16x32_bf16 v[52:55], v[156:159], v[180:183], v[52:55]
	v_mfma_f32_16x16x32_bf16 v[44:47], v[148:151], v[198:201], v[44:47]
	v_mfma_f32_16x16x32_bf16 v[36:39], v[156:159], v[198:201], v[36:39]
	v_mfma_f32_16x16x32_bf16 v[28:31], v[148:151], v[206:209], v[28:31]
	v_mfma_f32_16x16x32_bf16 v[20:23], v[156:159], v[206:209], v[20:23]
	v_mfma_f32_16x16x32_bf16 v[12:15], v[148:151], v[228:231], v[12:15]
	v_mfma_f32_16x16x32_bf16 v[4:7], v[156:159], v[228:231], v[4:7]
	s_setprio 0
	s_setprio 1
	v_mfma_f32_16x16x32_bf16 v[56:59], v[160:163], v[176:179], v[56:59]
	v_mfma_f32_16x16x32_bf16 v[48:51], v[168:171], v[176:179], v[48:51]
	v_mfma_f32_16x16x32_bf16 v[40:43], v[160:163], v[194:197], v[40:43]
	v_mfma_f32_16x16x32_bf16 v[32:35], v[168:171], v[194:197], v[32:35]
	v_mfma_f32_16x16x32_bf16 v[24:27], v[160:163], v[202:205], v[24:27]
	v_mfma_f32_16x16x32_bf16 v[16:19], v[168:171], v[202:205], v[16:19]
	v_mfma_f32_16x16x32_bf16 v[8:11], v[160:163], v[210:213], v[8:11]
	v_mfma_f32_16x16x32_bf16 v[0:3], v[168:171], v[210:213], v[0:3]
	s_setprio 0
	s_setprio 1
	v_mfma_f32_16x16x32_bf16 v[56:59], v[164:167], v[180:183], v[56:59]
	v_mfma_f32_16x16x32_bf16 v[48:51], v[172:175], v[180:183], v[48:51]
	v_mfma_f32_16x16x32_bf16 v[40:43], v[164:167], v[198:201], v[40:43]
	v_mfma_f32_16x16x32_bf16 v[32:35], v[172:175], v[198:201], v[32:35]
	v_mfma_f32_16x16x32_bf16 v[24:27], v[164:167], v[206:209], v[24:27]
	v_mfma_f32_16x16x32_bf16 v[16:19], v[172:175], v[206:209], v[16:19]
	v_mfma_f32_16x16x32_bf16 v[8:11], v[164:167], v[228:231], v[8:11]
	v_mfma_f32_16x16x32_bf16 v[0:3], v[172:175], v[228:231], v[0:3]
	s_setprio 0
	s_barrier
	s_add_i32 s52, 0, 0x18000
	s_add_i32 s53, 0, 0x1c000
	v_add_u32_e32 v156, s52, v141
	v_add_u32_e32 v172, s53, v141
	ds_read_b128 v[144:147], v156
	ds_read_b128 v[148:151], v156 offset:1024
	ds_read_b128 v[152:155], v156 offset:2048
	ds_read_b128 v[156:159], v156 offset:3072
	ds_read_b128 v[160:163], v172
	ds_read_b128 v[164:167], v172 offset:1024
	ds_read_b128 v[168:171], v172 offset:2048
	ds_read_b128 v[172:175], v172 offset:3072
	s_add_u32 s26, s26, 0x40000
	s_addc_u32 s27, s27, 0
	s_mov_b32 m0, s42
	v_lshl_add_u64 v[234:235], s[26:27], 0, v[134:135]
	ds_read_b128 v[176:179], v143 offset:32768
	ds_read_b128 v[180:183], v143 offset:33792
	ds_read_b128 v[194:197], v143 offset:34816
	ds_read_b128 v[198:201], v143 offset:35840
	ds_read_b128 v[202:205], v143 offset:36864
	ds_read_b128 v[206:209], v143 offset:37888
	ds_read_b128 v[210:213], v143 offset:38912
	ds_read_b128 v[228:231], v143 offset:39936
	global_load_lds_dwordx4 v[234:235], off
	v_lshl_add_u64 v[234:235], s[26:27], 0, v[130:131]
	s_mov_b32 m0, s43
	s_nop 0
	global_load_lds_dwordx4 v[234:235], off
	s_waitcnt vmcnt(8)
	s_waitcnt lgkmcnt(0)
	s_barrier
	s_setprio 1
	s_waitcnt lgkmcnt(0)
	v_mfma_f32_16x16x32_bf16 v[124:127], v[144:147], v[176:179], v[124:127]
	v_mfma_f32_16x16x32_bf16 v[116:119], v[152:155], v[176:179], v[116:119]
	v_mfma_f32_16x16x32_bf16 v[108:111], v[144:147], v[194:197], v[108:111]
	v_mfma_f32_16x16x32_bf16 v[100:103], v[152:155], v[194:197], v[100:103]
	v_mfma_f32_16x16x32_bf16 v[92:95], v[144:147], v[202:205], v[92:95]
	v_mfma_f32_16x16x32_bf16 v[84:87], v[152:155], v[202:205], v[84:87]
	v_mfma_f32_16x16x32_bf16 v[76:79], v[144:147], v[210:213], v[76:79]
	v_mfma_f32_16x16x32_bf16 v[68:71], v[152:155], v[210:213], v[68:71]
	s_setprio 0
	s_setprio 1
	v_mfma_f32_16x16x32_bf16 v[124:127], v[148:151], v[180:183], v[124:127]
	v_mfma_f32_16x16x32_bf16 v[116:119], v[156:159], v[180:183], v[116:119]
	v_mfma_f32_16x16x32_bf16 v[108:111], v[148:151], v[198:201], v[108:111]
	v_mfma_f32_16x16x32_bf16 v[100:103], v[156:159], v[198:201], v[100:103]
	v_mfma_f32_16x16x32_bf16 v[92:95], v[148:151], v[206:209], v[92:95]
	v_mfma_f32_16x16x32_bf16 v[84:87], v[156:159], v[206:209], v[84:87]
	v_mfma_f32_16x16x32_bf16 v[76:79], v[148:151], v[228:231], v[76:79]
	v_mfma_f32_16x16x32_bf16 v[68:71], v[156:159], v[228:231], v[68:71]
	s_setprio 0
	s_setprio 1
	v_mfma_f32_16x16x32_bf16 v[120:123], v[160:163], v[176:179], v[120:123]
	v_mfma_f32_16x16x32_bf16 v[112:115], v[168:171], v[176:179], v[112:115]
	v_mfma_f32_16x16x32_bf16 v[104:107], v[160:163], v[194:197], v[104:107]
	v_mfma_f32_16x16x32_bf16 v[96:99], v[168:171], v[194:197], v[96:99]
	v_mfma_f32_16x16x32_bf16 v[88:91], v[160:163], v[202:205], v[88:91]
	v_mfma_f32_16x16x32_bf16 v[80:83], v[168:171], v[202:205], v[80:83]
	v_mfma_f32_16x16x32_bf16 v[72:75], v[160:163], v[210:213], v[72:75]
	v_mfma_f32_16x16x32_bf16 v[64:67], v[168:171], v[210:213], v[64:67]
	s_setprio 0
	s_setprio 1
	v_mfma_f32_16x16x32_bf16 v[120:123], v[164:167], v[180:183], v[120:123]
	v_mfma_f32_16x16x32_bf16 v[112:115], v[172:175], v[180:183], v[112:115]
	v_mfma_f32_16x16x32_bf16 v[104:107], v[164:167], v[198:201], v[104:107]
	v_mfma_f32_16x16x32_bf16 v[96:99], v[172:175], v[198:201], v[96:99]
	v_mfma_f32_16x16x32_bf16 v[88:91], v[164:167], v[206:209], v[88:91]
	v_mfma_f32_16x16x32_bf16 v[80:83], v[172:175], v[206:209], v[80:83]
	v_mfma_f32_16x16x32_bf16 v[72:75], v[164:167], v[228:231], v[72:75]
	v_mfma_f32_16x16x32_bf16 v[64:67], v[172:175], v[228:231], v[64:67]
	s_setprio 0
	s_barrier
; #define PG8_STAGE(bufoff, gbase, voff) do { _Pragma("unroll") for (int _i = 0; _i < 2; ++_i) \
;         __builtin_amdgcn_global_load_lds((const unsigned*)((const char*)(gbase) + (voff)[_i]), (PG8_LAS unsigned*)(lds + (bufoff) + ldsw + _i * 8192), 16, 0, 0); } while (0)
; #define PG8_LDA(dst, b, h) do { _Pragma("unroll") for (int m = 0; m < 4; ++m) _Pragma("unroll") for (int k = 0; k < 2; ++k) dst[m][k] = *(const PG8_LAS bf16x8*)(lds + PG8_SA(b, h) + aoff + m * 2048 + k * 1024); } while (0)
; #define PG8_MMA(ai, bj, At, Bt) do { __builtin_amdgcn_s_setprio(1); _Pragma("unroll") for (int m = 0; m < 4; ++m) _Pragma("unroll") for (int n = 0; n < 2; ++n) _Pragma("unroll") for (int k = 0; k < 2; ++k) \
;         acc[ai][bj][m][n] = __builtin_amdgcn_mfma_f32_16x16x32_bf16(Bt[n][k], At[m][k], acc[ai][bj][m][n], 0, 0, 0); __builtin_amdgcn_s_setprio(0); } while (0)
; #define PG8_WAIT_V(n) asm volatile("s_waitcnt vmcnt(" #n ")" ::: "memory")
; #define PG8_WAIT_L(n) asm volatile("s_waitcnt lgkmcnt(" #n ")" ::: "memory")
; #define PG8_BAR __builtin_amdgcn_s_barrier()
; #define PG8_SCHED __builtin_amdgcn_sched_barrier(0)
; template <class Epi, class Sched, bool ALIGN_EPI = false, bool SP2 = false>
; __device__ __forceinline__ void gemm_phase(PG8_LAS unsigned char* lds, const Gemm g, const Sched& S, const Epi& E) {
;     ...
;             PG8_LDA(At, 1, 1); PG8_STAGE(PG8_SB(1, 0), b3, voffB); PG8_STAGE(PG8_SB(1, 1), b3 + hstep, voffB); PG8_STAGE(PG8_SA(1, 0), a3, voffA);
;             PG8_WAIT_V(8); PG8_WAIT_L(0); PG8_BAR; PG8_MMA(1, 0, At, B0); PG8_MMA(1, 1, At, B1); PG8_BAR; PG8_SCHED;
	s_add_i32 s26, s52, s39
	v_lshl_add_u64 v[214:215], v[214:215], 0, s[96:97]
	s_mov_b32 m0, s26
	ds_read_b128 v[176:179], v143 offset:49152
	ds_read_b128 v[180:183], v143 offset:50176
	ds_read_b128 v[194:197], v143 offset:51200
	ds_read_b128 v[198:201], v143 offset:52224
	ds_read_b128 v[202:205], v143 offset:53248
	ds_read_b128 v[206:209], v143 offset:54272
	ds_read_b128 v[210:213], v143 offset:55296
	ds_read_b128 v[228:231], v143 offset:56320
	global_load_lds_dwordx4 v[214:215], off
	s_add_i32 m0, s26, 0x2000
	s_add_u32 s24, s24, 0x40080
	v_lshl_add_u64 v[214:215], v[224:225], 0, s[96:97]
	s_addc_u32 s25, s25, 0
	s_add_i32 s26, s53, s39
	global_load_lds_dwordx4 v[214:215], off
	v_lshl_add_u64 v[214:215], s[24:25], 0, v[132:133]
	s_mov_b32 m0, s26
	s_nop 0
	global_load_lds_dwordx4 v[214:215], off
	v_lshl_add_u64 v[214:215], s[24:25], 0, v[128:129]
	s_add_i32 m0, s26, 0x2000
	s_nop 0
	global_load_lds_dwordx4 v[214:215], off
	v_lshl_add_u64 v[214:215], v[226:227], 0, s[96:97]
	s_mov_b32 m0, s44
	s_nop 0
	global_load_lds_dwordx4 v[214:215], off
	v_lshl_add_u64 v[214:215], v[232:233], 0, s[96:97]
	s_mov_b32 m0, s45
	s_nop 0
	global_load_lds_dwordx4 v[214:215], off
	s_waitcnt vmcnt(8)
	s_waitcnt lgkmcnt(0)
	s_barrier
	s_setprio 1
	s_waitcnt lgkmcnt(0)
	v_mfma_f32_16x16x32_bf16 v[60:63], v[144:147], v[176:179], v[60:63]
	v_mfma_f32_16x16x32_bf16 v[52:55], v[152:155], v[176:179], v[52:55]
	v_mfma_f32_16x16x32_bf16 v[44:47], v[144:147], v[194:197], v[44:47]
	v_mfma_f32_16x16x32_bf16 v[36:39], v[152:155], v[194:197], v[36:39]
	v_mfma_f32_16x16x32_bf16 v[28:31], v[144:147], v[202:205], v[28:31]
	v_mfma_f32_16x16x32_bf16 v[20:23], v[152:155], v[202:205], v[20:23]
	v_mfma_f32_16x16x32_bf16 v[12:15], v[144:147], v[210:213], v[12:15]
	v_mfma_f32_16x16x32_bf16 v[4:7], v[152:155], v[210:213], v[4:7]
	s_setprio 0
	s_setprio 1
	v_mfma_f32_16x16x32_bf16 v[60:63], v[148:151], v[180:183], v[60:63]
	v_mfma_f32_16x16x32_bf16 v[52:55], v[156:159], v[180:183], v[52:55]
	v_mfma_f32_16x16x32_bf16 v[44:47], v[148:151], v[198:201], v[44:47]
	v_mfma_f32_16x16x32_bf16 v[36:39], v[156:159], v[198:201], v[36:39]
	v_mfma_f32_16x16x32_bf16 v[28:31], v[148:151], v[206:209], v[28:31]
	v_mfma_f32_16x16x32_bf16 v[20:23], v[156:159], v[206:209], v[20:23]
	v_mfma_f32_16x16x32_bf16 v[12:15], v[148:151], v[228:231], v[12:15]
	v_mfma_f32_16x16x32_bf16 v[4:7], v[156:159], v[228:231], v[4:7]
	s_setprio 0
	s_setprio 1
	v_mfma_f32_16x16x32_bf16 v[56:59], v[160:163], v[176:179], v[56:59]
	v_mfma_f32_16x16x32_bf16 v[48:51], v[168:171], v[176:179], v[48:51]
	v_mfma_f32_16x16x32_bf16 v[40:43], v[160:163], v[194:197], v[40:43]
	v_mfma_f32_16x16x32_bf16 v[32:35], v[168:171], v[194:197], v[32:35]
	v_mfma_f32_16x16x32_bf16 v[24:27], v[160:163], v[202:205], v[24:27]
	v_mfma_f32_16x16x32_bf16 v[16:19], v[168:171], v[202:205], v[16:19]
	v_mfma_f32_16x16x32_bf16 v[8:11], v[160:163], v[210:213], v[8:11]
	v_mfma_f32_16x16x32_bf16 v[0:3], v[168:171], v[210:213], v[0:3]
	s_setprio 0
	s_setprio 1
	v_mfma_f32_16x16x32_bf16 v[56:59], v[164:167], v[180:183], v[56:59]
	v_mfma_f32_16x16x32_bf16 v[48:51], v[172:175], v[180:183], v[48:51]
	v_mfma_f32_16x16x32_bf16 v[40:43], v[164:167], v[198:201], v[40:43]
	v_mfma_f32_16x16x32_bf16 v[32:35], v[172:175], v[198:201], v[32:35]
	v_mfma_f32_16x16x32_bf16 v[24:27], v[164:167], v[206:209], v[24:27]
	v_mfma_f32_16x16x32_bf16 v[16:19], v[172:175], v[206:209], v[16:19]
	v_mfma_f32_16x16x32_bf16 v[8:11], v[164:167], v[228:231], v[8:11]
	v_mfma_f32_16x16x32_bf16 v[0:3], v[172:175], v[228:231], v[0:3]
	s_setprio 0
	s_barrier
	s_add_i32 s51, s51, 2
	s_add_u32 s0, s0, 0x100
	s_addc_u32 s1, s1, 0
	s_add_u32 s49, s49, 0x100
	s_addc_u32 s50, s50, 0
	s_cmp_gt_u32 s51, 13
	s_cbranch_scc0 .LBB0_35
	s_and_b64 vcc, exec, s[12:13]
	s_cbranch_vccz .LBB0_38
	s_barrier

; #define PG8_STAGE(bufoff, gbase, voff) do { _Pragma("unroll") for (int _i = 0; _i < 2; ++_i) \
;         __builtin_amdgcn_global_load_lds((const unsigned*)((const char*)(gbase) + (voff)[_i]), (PG8_LAS unsigned*)(lds + (bufoff) + ldsw + _i * 8192), 16, 0, 0); } while (0)
; #define PG8_LDA(dst, b, h) do { _Pragma("unroll") for (int m = 0; m < 4; ++m) _Pragma("unroll") for (int k = 0; k < 2; ++k) dst[m][k] = *(const PG8_LAS bf16x8*)(lds + PG8_SA(b, h) + aoff + m * 2048 + k * 1024); } while (0)
; #define PG8_LDB(dst, b, h) do { _Pragma("unroll") for (int n = 0; n < 2; ++n) _Pragma("unroll") for (int k = 0; k < 2; ++k) dst[n][k] = *(const PG8_LAS bf16x8*)(lds + PG8_SB(b, h) + boff + n * 2048 + k * 1024); } while (0)
; #define PG8_MMA(ai, bj, At, Bt) do { __builtin_amdgcn_s_setprio(1); _Pragma("unroll") for (int m = 0; m < 4; ++m) _Pragma("unroll") for (int n = 0; n < 2; ++n) _Pragma("unroll") for (int k = 0; k < 2; ++k) \
;         acc[ai][bj][m][n] = __builtin_amdgcn_mfma_f32_16x16x32_bf16(Bt[n][k], At[m][k], acc[ai][bj][m][n], 0, 0, 0); __builtin_amdgcn_s_setprio(0); } while (0)
; #define PG8_WAIT_V(n) asm volatile("s_waitcnt vmcnt(" #n ")" ::: "memory")
; #define PG8_WAIT_L(n) asm volatile("s_waitcnt lgkmcnt(" #n ")" ::: "memory")
; #define PG8_BAR __builtin_amdgcn_s_barrier()
; #define PG8_SCHED __builtin_amdgcn_sched_barrier(0)
; template <class Epi, class Sched, bool ALIGN_EPI = false, bool SP2 = false>
; __device__ __forceinline__ void gemm_phase(PG8_LAS unsigned char* lds, const Gemm g, const Sched& S, const Epi& E) {
;     ...
;         for (int t = 0; t < nt; t += 2) {
;             const bool last = (t == nt - 2);
;             const char* a1 = cA + (size_t)(t + 1) * kstep;
;             const char* a2 = last ? nA : cA + (size_t)(t + 2) * kstep; const char* b2 = last ? nB : cB + (size_t)(t + 2) * kstep;
;             const char* a3 = a2 + kstep; const char* b3 = b2 + kstep;
;             if (last && has_next) S.a_ready(nxt);
;             if constexpr (SP2) {
;             PG8_LDB(B0, 0, 0); PG8_LDB(B1, 0, 1); PG8_SCHED; PG8_LDA(At, 0, 0); PG8_STAGE(PG8_SA(1, 1), a1 + hstep, voffA);
;             PG8_WAIT_V(8); PG8_WAIT_L(0); PG8_BAR; PG8_MMA(0, 0, At, B0); PG8_MMA(0, 1, At, B1); PG8_BAR; PG8_SCHED;
;             PG8_LDA(At, 0, 1); PG8_STAGE(PG8_SB(0, 0), b2, voffB); PG8_STAGE(PG8_SB(0, 1), b2 + hstep, voffB); PG8_STAGE(PG8_SA(0, 0), a2, voffA);
.LBB0_218:
	s_add_u32 s25, s0, 0xfffc0080
	s_addc_u32 s40, s1, -1
	s_add_i32 s94, 0, 0x10000
	s_cmp_eq_u32 s93, 12
	s_cselect_b32 s43, s4, s40
	s_cselect_b32 s42, s5, s25
	s_cselect_b32 s41, s27, s92
	s_cselect_b32 s40, s58, s59
	s_add_i32 s25, 0, 0x14000
	v_add_u32_e32 v140, s94, v228
	v_add_u32_e32 v156, s25, v228
	ds_read_b128 v[128:131], v140
	ds_read_b128 v[132:135], v140 offset:1024
	ds_read_b128 v[136:139], v140 offset:2048
	ds_read_b128 v[140:143], v140 offset:3072
	ds_read_b128 v[144:147], v156
	ds_read_b128 v[148:151], v156 offset:1024
	ds_read_b128 v[152:155], v156 offset:2048
	ds_read_b128 v[156:159], v156 offset:3072
	v_lshl_add_u64 v[212:213], s[0:1], 0, v[200:201]
	s_add_i32 m0, s45, 0xc000
	ds_read_b128 v[160:163], v230
	ds_read_b128 v[164:167], v230 offset:1024
	ds_read_b128 v[168:171], v230 offset:2048
	ds_read_b128 v[172:175], v230 offset:3072
	ds_read_b128 v[176:179], v230 offset:4096
	ds_read_b128 v[180:183], v230 offset:5120
	ds_read_b128 v[204:207], v230 offset:6144
	ds_read_b128 v[208:211], v230 offset:7168
	global_load_lds_dwordx4 v[212:213], off
	v_lshl_add_u64 v[212:213], s[0:1], 0, v[202:203]
	s_add_i32 m0, s45, 0xe000
	s_nop 0
	global_load_lds_dwordx4 v[212:213], off
	s_waitcnt vmcnt(8)
	s_waitcnt lgkmcnt(0)
	s_barrier
	s_setprio 1
	s_waitcnt lgkmcnt(0)
	v_mfma_f32_16x16x32_bf16 v[124:127], v[128:131], v[160:163], v[124:127]
	v_mfma_f32_16x16x32_bf16 v[120:123], v[136:139], v[160:163], v[120:123]
	v_mfma_f32_16x16x32_bf16 v[108:111], v[128:131], v[168:171], v[108:111]
	v_mfma_f32_16x16x32_bf16 v[104:107], v[136:139], v[168:171], v[104:107]
	v_mfma_f32_16x16x32_bf16 v[92:95], v[128:131], v[176:179], v[92:95]
	v_mfma_f32_16x16x32_bf16 v[88:91], v[136:139], v[176:179], v[88:91]
	v_mfma_f32_16x16x32_bf16 v[76:79], v[128:131], v[204:207], v[76:79]
	v_mfma_f32_16x16x32_bf16 v[72:75], v[136:139], v[204:207], v[72:75]
	s_setprio 0
	s_setprio 1
	v_mfma_f32_16x16x32_bf16 v[124:127], v[132:135], v[164:167], v[124:127]
	v_mfma_f32_16x16x32_bf16 v[120:123], v[140:143], v[164:167], v[120:123]
	v_mfma_f32_16x16x32_bf16 v[108:111], v[132:135], v[172:175], v[108:111]
	v_mfma_f32_16x16x32_bf16 v[104:107], v[140:143], v[172:175], v[104:107]
	v_mfma_f32_16x16x32_bf16 v[92:95], v[132:135], v[180:183], v[92:95]
	v_mfma_f32_16x16x32_bf16 v[88:91], v[140:143], v[180:183], v[88:91]
	v_mfma_f32_16x16x32_bf16 v[76:79], v[132:135], v[208:211], v[76:79]
	v_mfma_f32_16x16x32_bf16 v[72:75], v[140:143], v[208:211], v[72:75]
	s_setprio 0
	s_setprio 1
	v_mfma_f32_16x16x32_bf16 v[116:119], v[144:147], v[160:163], v[116:119]
	v_mfma_f32_16x16x32_bf16 v[112:115], v[152:155], v[160:163], v[112:115]
	v_mfma_f32_16x16x32_bf16 v[100:103], v[144:147], v[168:171], v[100:103]
	v_mfma_f32_16x16x32_bf16 v[96:99], v[152:155], v[168:171], v[96:99]
	v_mfma_f32_16x16x32_bf16 v[84:87], v[144:147], v[176:179], v[84:87]
	v_mfma_f32_16x16x32_bf16 v[80:83], v[152:155], v[176:179], v[80:83]
	v_mfma_f32_16x16x32_bf16 v[68:71], v[144:147], v[204:207], v[68:71]
	v_mfma_f32_16x16x32_bf16 v[64:67], v[152:155], v[204:207], v[64:67]
	s_setprio 0
	s_setprio 1
	v_mfma_f32_16x16x32_bf16 v[116:119], v[148:151], v[164:167], v[116:119]
	v_mfma_f32_16x16x32_bf16 v[112:115], v[156:159], v[164:167], v[112:115]
	v_mfma_f32_16x16x32_bf16 v[100:103], v[148:151], v[172:175], v[100:103]
	v_mfma_f32_16x16x32_bf16 v[96:99], v[156:159], v[172:175], v[96:99]
	v_mfma_f32_16x16x32_bf16 v[84:87], v[148:151], v[180:183], v[84:87]
	v_mfma_f32_16x16x32_bf16 v[80:83], v[156:159], v[180:183], v[80:83]
	v_mfma_f32_16x16x32_bf16 v[68:71], v[148:151], v[208:211], v[68:71]
	v_mfma_f32_16x16x32_bf16 v[64:67], v[156:159], v[208:211], v[64:67]
	s_setprio 0
	s_barrier
	s_add_i32 s94, s94, s44
	v_lshl_add_u64 v[212:213], s[40:41], 0, v[184:185]
	s_mov_b32 m0, s94
	ds_read_b128 v[160:163], v230 offset:16384
	ds_read_b128 v[164:167], v230 offset:17408
	ds_read_b128 v[168:171], v230 offset:18432
	ds_read_b128 v[172:175], v230 offset:19456
	ds_read_b128 v[176:179], v230 offset:20480
	ds_read_b128 v[180:183], v230 offset:21504
	ds_read_b128 v[204:207], v230 offset:22528
	ds_read_b128 v[208:211], v230 offset:23552
	global_load_lds_dwordx4 v[212:213], off
	s_add_i32 m0, s94, 0x2000
	s_add_u32 s94, s40, 0x40000
	v_lshl_add_u64 v[214:215], s[40:41], 0, v[194:195]
	s_addc_u32 s95, s41, 0
	s_add_i32 s25, s25, s44
	global_load_lds_dwordx4 v[214:215], off
	v_lshl_add_u64 v[224:225], s[94:95], 0, v[184:185]
	s_mov_b32 m0, s25
	v_lshl_add_u64 v[232:233], s[42:43], 0, v[196:197]
	global_load_lds_dwordx4 v[224:225], off
	v_lshl_add_u64 v[224:225], s[94:95], 0, v[194:195]
	s_add_i32 m0, s25, 0x2000
	s_nop 0
	global_load_lds_dwordx4 v[224:225], off
	v_lshl_add_u64 v[224:225], s[42:43], 0, v[198:199]
	s_mov_b32 m0, s45
	s_nop 0
	global_load_lds_dwordx4 v[224:225], off
	s_mov_b32 m0, s46
	s_nop 0
	global_load_lds_dwordx4 v[232:233], off
	s_waitcnt vmcnt(8)
	s_waitcnt lgkmcnt(0)
	s_barrier
; #define PG8_STAGE(bufoff, gbase, voff) do { _Pragma("unroll") for (int _i = 0; _i < 2; ++_i) \
;         __builtin_amdgcn_global_load_lds((const unsigned*)((const char*)(gbase) + (voff)[_i]), (PG8_LAS unsigned*)(lds + (bufoff) + ldsw + _i * 8192), 16, 0, 0); } while (0)
; #define PG8_LDA(dst, b, h) do { _Pragma("unroll") for (int m = 0; m < 4; ++m) _Pragma("unroll") for (int k = 0; k < 2; ++k) dst[m][k] = *(const PG8_LAS bf16x8*)(lds + PG8_SA(b, h) + aoff + m * 2048 + k * 1024); } while (0)
; #define PG8_LDB(dst, b, h) do { _Pragma("unroll") for (int n = 0; n < 2; ++n) _Pragma("unroll") for (int k = 0; k < 2; ++k) dst[n][k] = *(const PG8_LAS bf16x8*)(lds + PG8_SB(b, h) + boff + n * 2048 + k * 1024); } while (0)
; #define PG8_MMA(ai, bj, At, Bt) do { __builtin_amdgcn_s_setprio(1); _Pragma("unroll") for (int m = 0; m < 4; ++m) _Pragma("unroll") for (int n = 0; n < 2; ++n) _Pragma("unroll") for (int k = 0; k < 2; ++k) \
;         acc[ai][bj][m][n] = __builtin_amdgcn_mfma_f32_16x16x32_bf16(Bt[n][k], At[m][k], acc[ai][bj][m][n], 0, 0, 0); __builtin_amdgcn_s_setprio(0); } while (0)
; #define PG8_WAIT_V(n) asm volatile("s_waitcnt vmcnt(" #n ")" ::: "memory")
; #define PG8_WAIT_L(n) asm volatile("s_waitcnt lgkmcnt(" #n ")" ::: "memory")
; #define PG8_BAR __builtin_amdgcn_s_barrier()
; #define PG8_SCHED __builtin_amdgcn_sched_barrier(0)
; template <class Epi, class Sched, bool ALIGN_EPI = false, bool SP2 = false>
; __device__ __forceinline__ void gemm_phase(PG8_LAS unsigned char* lds, const Gemm g, const Sched& S, const Epi& E) {
;     ...
;             PG8_WAIT_V(8); PG8_WAIT_L(0); PG8_BAR; PG8_MMA(1, 0, At, B0); PG8_MMA(1, 1, At, B1); PG8_BAR; PG8_SCHED;
;             PG8_LDB(B0, 1, 0); PG8_LDB(B1, 1, 1); PG8_SCHED; PG8_LDA(At, 1, 0); PG8_STAGE(PG8_SA(0, 1), a2 + hstep, voffA);
;             PG8_WAIT_V(8); PG8_WAIT_L(0); PG8_BAR; PG8_MMA(0, 0, At, B0); PG8_MMA(0, 1, At, B1); PG8_BAR; PG8_SCHED;
	s_setprio 1
	s_waitcnt lgkmcnt(0)
	v_mfma_f32_16x16x32_bf16 v[60:63], v[128:131], v[160:163], v[60:63]
	v_mfma_f32_16x16x32_bf16 v[56:59], v[136:139], v[160:163], v[56:59]
	v_mfma_f32_16x16x32_bf16 v[44:47], v[128:131], v[168:171], v[44:47]
	v_mfma_f32_16x16x32_bf16 v[40:43], v[136:139], v[168:171], v[40:43]
	v_mfma_f32_16x16x32_bf16 v[28:31], v[128:131], v[176:179], v[28:31]
	v_mfma_f32_16x16x32_bf16 v[24:27], v[136:139], v[176:179], v[24:27]
	v_mfma_f32_16x16x32_bf16 v[12:15], v[128:131], v[204:207], v[12:15]
	v_mfma_f32_16x16x32_bf16 v[8:11], v[136:139], v[204:207], v[8:11]
	s_setprio 0
	s_setprio 1
	v_mfma_f32_16x16x32_bf16 v[60:63], v[132:135], v[164:167], v[60:63]
	v_mfma_f32_16x16x32_bf16 v[56:59], v[140:143], v[164:167], v[56:59]
	v_mfma_f32_16x16x32_bf16 v[44:47], v[132:135], v[172:175], v[44:47]
	v_mfma_f32_16x16x32_bf16 v[40:43], v[140:143], v[172:175], v[40:43]
	v_mfma_f32_16x16x32_bf16 v[28:31], v[132:135], v[180:183], v[28:31]
	v_mfma_f32_16x16x32_bf16 v[24:27], v[140:143], v[180:183], v[24:27]
	v_mfma_f32_16x16x32_bf16 v[12:15], v[132:135], v[208:211], v[12:15]
	v_mfma_f32_16x16x32_bf16 v[8:11], v[140:143], v[208:211], v[8:11]
	s_setprio 0
	s_setprio 1
	v_mfma_f32_16x16x32_bf16 v[52:55], v[144:147], v[160:163], v[52:55]
	v_mfma_f32_16x16x32_bf16 v[48:51], v[152:155], v[160:163], v[48:51]
	v_mfma_f32_16x16x32_bf16 v[36:39], v[144:147], v[168:171], v[36:39]
	v_mfma_f32_16x16x32_bf16 v[32:35], v[152:155], v[168:171], v[32:35]
	v_mfma_f32_16x16x32_bf16 v[20:23], v[144:147], v[176:179], v[20:23]
	v_mfma_f32_16x16x32_bf16 v[16:19], v[152:155], v[176:179], v[16:19]
	v_mfma_f32_16x16x32_bf16 v[4:7], v[144:147], v[204:207], v[4:7]
	v_mfma_f32_16x16x32_bf16 v[0:3], v[152:155], v[204:207], v[0:3]
	s_setprio 0
	s_setprio 1
	v_mfma_f32_16x16x32_bf16 v[52:55], v[148:151], v[164:167], v[52:55]
	v_mfma_f32_16x16x32_bf16 v[48:51], v[156:159], v[164:167], v[48:51]
	v_mfma_f32_16x16x32_bf16 v[36:39], v[148:151], v[172:175], v[36:39]
	v_mfma_f32_16x16x32_bf16 v[32:35], v[156:159], v[172:175], v[32:35]
	v_mfma_f32_16x16x32_bf16 v[20:23], v[148:151], v[180:183], v[20:23]
	v_mfma_f32_16x16x32_bf16 v[16:19], v[156:159], v[180:183], v[16:19]
	v_mfma_f32_16x16x32_bf16 v[4:7], v[148:151], v[208:211], v[4:7]
	v_mfma_f32_16x16x32_bf16 v[0:3], v[156:159], v[208:211], v[0:3]
	s_setprio 0
	s_barrier
	s_add_i32 s25, 0, 0x18000
	s_add_i32 s94, 0, 0x1c000
	v_add_u32_e32 v140, s25, v228
	v_add_u32_e32 v156, s94, v228
	ds_read_b128 v[128:131], v140
	ds_read_b128 v[132:135], v140 offset:1024
	ds_read_b128 v[136:139], v140 offset:2048
	ds_read_b128 v[140:143], v140 offset:3072
	ds_read_b128 v[144:147], v156
	ds_read_b128 v[148:151], v156 offset:1024
	ds_read_b128 v[152:155], v156 offset:2048
	ds_read_b128 v[156:159], v156 offset:3072
	s_add_u32 s42, s42, 0x40000
	s_addc_u32 s43, s43, 0
	s_mov_b32 m0, s47
	v_lshl_add_u64 v[234:235], s[42:43], 0, v[198:199]
	ds_read_b128 v[160:163], v230 offset:32768
	ds_read_b128 v[164:167], v230 offset:33792
	ds_read_b128 v[168:171], v230 offset:34816
	ds_read_b128 v[172:175], v230 offset:35840
	ds_read_b128 v[176:179], v230 offset:36864
	ds_read_b128 v[180:183], v230 offset:37888
	ds_read_b128 v[204:207], v230 offset:38912
	ds_read_b128 v[208:211], v230 offset:39936
	global_load_lds_dwordx4 v[234:235], off
	v_lshl_add_u64 v[234:235], s[42:43], 0, v[196:197]
	s_mov_b32 m0, s48
	s_nop 0
	global_load_lds_dwordx4 v[234:235], off
	s_waitcnt vmcnt(8)
	s_waitcnt lgkmcnt(0)
	s_barrier
	s_setprio 1
	s_waitcnt lgkmcnt(0)
	v_mfma_f32_16x16x32_bf16 v[124:127], v[128:131], v[160:163], v[124:127]
	v_mfma_f32_16x16x32_bf16 v[120:123], v[136:139], v[160:163], v[120:123]
	v_mfma_f32_16x16x32_bf16 v[108:111], v[128:131], v[168:171], v[108:111]
	v_mfma_f32_16x16x32_bf16 v[104:107], v[136:139], v[168:171], v[104:107]
	v_mfma_f32_16x16x32_bf16 v[92:95], v[128:131], v[176:179], v[92:95]
	v_mfma_f32_16x16x32_bf16 v[88:91], v[136:139], v[176:179], v[88:91]
	v_mfma_f32_16x16x32_bf16 v[76:79], v[128:131], v[204:207], v[76:79]
	v_mfma_f32_16x16x32_bf16 v[72:75], v[136:139], v[204:207], v[72:75]
	s_setprio 0
	s_setprio 1
	v_mfma_f32_16x16x32_bf16 v[124:127], v[132:135], v[164:167], v[124:127]
	v_mfma_f32_16x16x32_bf16 v[120:123], v[140:143], v[164:167], v[120:123]
	v_mfma_f32_16x16x32_bf16 v[108:111], v[132:135], v[172:175], v[108:111]
	v_mfma_f32_16x16x32_bf16 v[104:107], v[140:143], v[172:175], v[104:107]
	v_mfma_f32_16x16x32_bf16 v[92:95], v[132:135], v[180:183], v[92:95]
	v_mfma_f32_16x16x32_bf16 v[88:91], v[140:143], v[180:183], v[88:91]
	v_mfma_f32_16x16x32_bf16 v[76:79], v[132:135], v[208:211], v[76:79]
	v_mfma_f32_16x16x32_bf16 v[72:75], v[140:143], v[208:211], v[72:75]
	s_setprio 0
	s_setprio 1
	v_mfma_f32_16x16x32_bf16 v[116:119], v[144:147], v[160:163], v[116:119]
	v_mfma_f32_16x16x32_bf16 v[112:115], v[152:155], v[160:163], v[112:115]
	v_mfma_f32_16x16x32_bf16 v[100:103], v[144:147], v[168:171], v[100:103]
	v_mfma_f32_16x16x32_bf16 v[96:99], v[152:155], v[168:171], v[96:99]
	v_mfma_f32_16x16x32_bf16 v[84:87], v[144:147], v[176:179], v[84:87]
	v_mfma_f32_16x16x32_bf16 v[80:83], v[152:155], v[176:179], v[80:83]
	v_mfma_f32_16x16x32_bf16 v[68:71], v[144:147], v[204:207], v[68:71]
	v_mfma_f32_16x16x32_bf16 v[64:67], v[152:155], v[204:207], v[64:67]
	s_setprio 0
	s_setprio 1
	v_mfma_f32_16x16x32_bf16 v[116:119], v[148:151], v[164:167], v[116:119]
	v_mfma_f32_16x16x32_bf16 v[112:115], v[156:159], v[164:167], v[112:115]
	v_mfma_f32_16x16x32_bf16 v[100:103], v[148:151], v[172:175], v[100:103]
	v_mfma_f32_16x16x32_bf16 v[96:99], v[156:159], v[172:175], v[96:99]
	v_mfma_f32_16x16x32_bf16 v[84:87], v[148:151], v[180:183], v[84:87]
	v_mfma_f32_16x16x32_bf16 v[80:83], v[156:159], v[180:183], v[80:83]
	v_mfma_f32_16x16x32_bf16 v[68:71], v[148:151], v[208:211], v[68:71]
	v_mfma_f32_16x16x32_bf16 v[64:67], v[156:159], v[208:211], v[64:67]
	s_setprio 0
	s_barrier
; #define PG8_STAGE(bufoff, gbase, voff) do { _Pragma("unroll") for (int _i = 0; _i < 2; ++_i) \
;         __builtin_amdgcn_global_load_lds((const unsigned*)((const char*)(gbase) + (voff)[_i]), (PG8_LAS unsigned*)(lds + (bufoff) + ldsw + _i * 8192), 16, 0, 0); } while (0)
; #define PG8_LDA(dst, b, h) do { _Pragma("unroll") for (int m = 0; m < 4; ++m) _Pragma("unroll") for (int k = 0; k < 2; ++k) dst[m][k] = *(const PG8_LAS bf16x8*)(lds + PG8_SA(b, h) + aoff + m * 2048 + k * 1024); } while (0)
; #define PG8_MMA(ai, bj, At, Bt) do { __builtin_amdgcn_s_setprio(1); _Pragma("unroll") for (int m = 0; m < 4; ++m) _Pragma("unroll") for (int n = 0; n < 2; ++n) _Pragma("unroll") for (int k = 0; k < 2; ++k) \
;         acc[ai][bj][m][n] = __builtin_amdgcn_mfma_f32_16x16x32_bf16(Bt[n][k], At[m][k], acc[ai][bj][m][n], 0, 0, 0); __builtin_amdgcn_s_setprio(0); } while (0)
; #define PG8_WAIT_V(n) asm volatile("s_waitcnt vmcnt(" #n ")" ::: "memory")
; #define PG8_WAIT_L(n) asm volatile("s_waitcnt lgkmcnt(" #n ")" ::: "memory")
; #define PG8_BAR __builtin_amdgcn_s_barrier()
; #define PG8_SCHED __builtin_amdgcn_sched_barrier(0)
; template <class Epi, class Sched, bool ALIGN_EPI = false, bool SP2 = false>
; __device__ __forceinline__ void gemm_phase(PG8_LAS unsigned char* lds, const Gemm g, const Sched& S, const Epi& E) {
;     ...
;             PG8_LDA(At, 1, 1); PG8_STAGE(PG8_SB(1, 0), b3, voffB); PG8_STAGE(PG8_SB(1, 1), b3 + hstep, voffB); PG8_STAGE(PG8_SA(1, 0), a3, voffA);
;             PG8_WAIT_V(8); PG8_WAIT_L(0); PG8_BAR; PG8_MMA(1, 0, At, B0); PG8_MMA(1, 1, At, B1); PG8_BAR; PG8_SCHED;
	s_add_i32 s42, s25, s44
	v_lshl_add_u64 v[212:213], v[212:213], 0, s[96:97]
	s_mov_b32 m0, s42
	ds_read_b128 v[160:163], v230 offset:49152
	ds_read_b128 v[164:167], v230 offset:50176
	ds_read_b128 v[168:171], v230 offset:51200
	ds_read_b128 v[172:175], v230 offset:52224
	ds_read_b128 v[176:179], v230 offset:53248
	ds_read_b128 v[180:183], v230 offset:54272
	ds_read_b128 v[204:207], v230 offset:55296
	ds_read_b128 v[208:211], v230 offset:56320
	global_load_lds_dwordx4 v[212:213], off
	s_add_i32 m0, s42, 0x2000
	s_add_u32 s40, s40, 0x40080
	v_lshl_add_u64 v[212:213], v[214:215], 0, s[96:97]
	s_addc_u32 s41, s41, 0
	s_add_i32 s42, s94, s44
	global_load_lds_dwordx4 v[212:213], off
	v_lshl_add_u64 v[212:213], s[40:41], 0, v[184:185]
	s_mov_b32 m0, s42
	s_nop 0
	global_load_lds_dwordx4 v[212:213], off
	v_lshl_add_u64 v[212:213], s[40:41], 0, v[194:195]
	s_add_i32 m0, s42, 0x2000
	s_nop 0
	global_load_lds_dwordx4 v[212:213], off
	v_lshl_add_u64 v[212:213], v[224:225], 0, s[96:97]
	s_mov_b32 m0, s51
	s_nop 0
	global_load_lds_dwordx4 v[212:213], off
	v_lshl_add_u64 v[212:213], v[232:233], 0, s[96:97]
	s_mov_b32 m0, s52
	s_nop 0
	global_load_lds_dwordx4 v[212:213], off
	s_waitcnt vmcnt(8)
	s_waitcnt lgkmcnt(0)
	s_barrier
	s_setprio 1
	s_waitcnt lgkmcnt(0)
	v_mfma_f32_16x16x32_bf16 v[60:63], v[128:131], v[160:163], v[60:63]
	v_mfma_f32_16x16x32_bf16 v[56:59], v[136:139], v[160:163], v[56:59]
	v_mfma_f32_16x16x32_bf16 v[44:47], v[128:131], v[168:171], v[44:47]
	v_mfma_f32_16x16x32_bf16 v[40:43], v[136:139], v[168:171], v[40:43]
	v_mfma_f32_16x16x32_bf16 v[28:31], v[128:131], v[176:179], v[28:31]
	v_mfma_f32_16x16x32_bf16 v[24:27], v[136:139], v[176:179], v[24:27]
	v_mfma_f32_16x16x32_bf16 v[12:15], v[128:131], v[204:207], v[12:15]
	v_mfma_f32_16x16x32_bf16 v[8:11], v[136:139], v[204:207], v[8:11]
	s_setprio 0
	s_setprio 1
	v_mfma_f32_16x16x32_bf16 v[60:63], v[132:135], v[164:167], v[60:63]
	v_mfma_f32_16x16x32_bf16 v[56:59], v[140:143], v[164:167], v[56:59]
	v_mfma_f32_16x16x32_bf16 v[44:47], v[132:135], v[172:175], v[44:47]
	v_mfma_f32_16x16x32_bf16 v[40:43], v[140:143], v[172:175], v[40:43]
	v_mfma_f32_16x16x32_bf16 v[28:31], v[132:135], v[180:183], v[28:31]
	v_mfma_f32_16x16x32_bf16 v[24:27], v[140:143], v[180:183], v[24:27]
	v_mfma_f32_16x16x32_bf16 v[12:15], v[132:135], v[208:211], v[12:15]
	v_mfma_f32_16x16x32_bf16 v[8:11], v[140:143], v[208:211], v[8:11]
	s_setprio 0
	s_setprio 1
	v_mfma_f32_16x16x32_bf16 v[52:55], v[144:147], v[160:163], v[52:55]
	v_mfma_f32_16x16x32_bf16 v[48:51], v[152:155], v[160:163], v[48:51]
	v_mfma_f32_16x16x32_bf16 v[36:39], v[144:147], v[168:171], v[36:39]
	v_mfma_f32_16x16x32_bf16 v[32:35], v[152:155], v[168:171], v[32:35]
	v_mfma_f32_16x16x32_bf16 v[20:23], v[144:147], v[176:179], v[20:23]
	v_mfma_f32_16x16x32_bf16 v[16:19], v[152:155], v[176:179], v[16:19]
	v_mfma_f32_16x16x32_bf16 v[4:7], v[144:147], v[204:207], v[4:7]
	v_mfma_f32_16x16x32_bf16 v[0:3], v[152:155], v[204:207], v[0:3]
	s_setprio 0
	s_setprio 1
	v_mfma_f32_16x16x32_bf16 v[52:55], v[148:151], v[164:167], v[52:55]
	v_mfma_f32_16x16x32_bf16 v[48:51], v[156:159], v[164:167], v[48:51]
	v_mfma_f32_16x16x32_bf16 v[36:39], v[148:151], v[172:175], v[36:39]
	v_mfma_f32_16x16x32_bf16 v[32:35], v[156:159], v[172:175], v[32:35]
	v_mfma_f32_16x16x32_bf16 v[20:23], v[148:151], v[180:183], v[20:23]
	v_mfma_f32_16x16x32_bf16 v[16:19], v[156:159], v[180:183], v[16:19]
	v_mfma_f32_16x16x32_bf16 v[4:7], v[148:151], v[208:211], v[4:7]
	v_mfma_f32_16x16x32_bf16 v[0:3], v[156:159], v[208:211], v[0:3]
	s_setprio 0
	s_barrier
	s_add_i32 s93, s93, 2
	s_add_u32 s0, s0, 0x100
	s_addc_u32 s1, s1, 0
	s_add_u32 s59, s59, 0x100
	s_addc_u32 s92, s92, 0
	s_cmp_gt_u32 s93, 13
	s_cbranch_scc0 .LBB0_218
	s_and_b64 vcc, exec, s[20:21]
	s_cbranch_vccz .LBB0_221
	s_barrier

; #define PG8_STAGE(bufoff, gbase, voff) do { _Pragma("unroll") for (int _i = 0; _i < 2; ++_i) \
;         __builtin_amdgcn_global_load_lds((const unsigned*)((const char*)(gbase) + (voff)[_i]), (PG8_LAS unsigned*)(lds + (bufoff) + ldsw + _i * 8192), 16, 0, 0); } while (0)
; #define PG8_LDA(dst, b, h) do { _Pragma("unroll") for (int m = 0; m < 4; ++m) _Pragma("unroll") for (int k = 0; k < 2; ++k) dst[m][k] = *(const PG8_LAS bf16x8*)(lds + PG8_SA(b, h) + aoff + m * 2048 + k * 1024); } while (0)
; #define PG8_LDB(dst, b, h) do { _Pragma("unroll") for (int n = 0; n < 2; ++n) _Pragma("unroll") for (int k = 0; k < 2; ++k) dst[n][k] = *(const PG8_LAS bf16x8*)(lds + PG8_SB(b, h) + boff + n * 2048 + k * 1024); } while (0)
; #define PG8_MMA(ai, bj, At, Bt) do { __builtin_amdgcn_s_setprio(1); _Pragma("unroll") for (int m = 0; m < 4; ++m) _Pragma("unroll") for (int n = 0; n < 2; ++n) _Pragma("unroll") for (int k = 0; k < 2; ++k) \
;         acc[ai][bj][m][n] = __builtin_amdgcn_mfma_f32_16x16x32_bf16(Bt[n][k], At[m][k], acc[ai][bj][m][n], 0, 0, 0); __builtin_amdgcn_s_setprio(0); } while (0)
; #define PG8_WAIT_V(n) asm volatile("s_waitcnt vmcnt(" #n ")" ::: "memory")
; #define PG8_WAIT_L(n) asm volatile("s_waitcnt lgkmcnt(" #n ")" ::: "memory")
; #define PG8_BAR __builtin_amdgcn_s_barrier()
; #define PG8_SCHED __builtin_amdgcn_sched_barrier(0)
; template <class Epi, class Sched, bool ALIGN_EPI = false, bool SP2 = false>
; __device__ __forceinline__ void gemm_phase(PG8_LAS unsigned char* lds, const Gemm g, const Sched& S, const Epi& E) {
;     ...
;         for (int t = 0; t < nt; t += 2) {
;             const bool last = (t == nt - 2);
;             const char* a1 = cA + (size_t)(t + 1) * kstep;
;             const char* a2 = last ? nA : cA + (size_t)(t + 2) * kstep; const char* b2 = last ? nB : cB + (size_t)(t + 2) * kstep;
;             const char* a3 = a2 + kstep; const char* b3 = b2 + kstep;
;             if (last && has_next) S.a_ready(nxt);
;             if constexpr (SP2) {
;             PG8_LDB(B0, 0, 0); PG8_LDB(B1, 0, 1); PG8_SCHED; PG8_LDA(At, 0, 0); PG8_STAGE(PG8_SA(1, 1), a1 + hstep, voffA);
;             PG8_WAIT_V(8); PG8_WAIT_L(0); PG8_BAR; PG8_MMA(0, 0, At, B0); PG8_MMA(0, 1, At, B1); PG8_BAR; PG8_SCHED;
;             PG8_LDA(At, 0, 1); PG8_STAGE(PG8_SB(0, 0), b2, voffB); PG8_STAGE(PG8_SB(0, 1), b2 + hstep, voffB); PG8_STAGE(PG8_SA(0, 0), a2, voffA);
.LBB0_461:
	s_add_u32 s0, s22, 0x100
	s_addc_u32 s1, s23, 0
	s_cmp_eq_u32 s50, 40
	s_cselect_b32 s27, s19, s1
	s_cselect_b32 s26, s18, s0
	s_cselect_b32 s25, s21, s5
	s_cselect_b32 s24, s20, s4
	s_add_i32 s6, 0, 0x10000
	s_add_i32 s51, 0, 0x14000
	v_add_u32_e32 v140, s6, v228
	v_add_u32_e32 v156, s51, v228
	ds_read_b128 v[128:131], v140
	ds_read_b128 v[132:135], v140 offset:1024
	ds_read_b128 v[136:139], v140 offset:2048
	ds_read_b128 v[140:143], v140 offset:3072
	ds_read_b128 v[144:147], v156
	ds_read_b128 v[148:151], v156 offset:1024
	ds_read_b128 v[152:155], v156 offset:2048
	ds_read_b128 v[156:159], v156 offset:3072
	s_add_u32 s98, s22, 0xb0080
	s_addc_u32 s99, s23, 0
	s_add_i32 m0, s30, 0xc000
	ds_read_b128 v[160:163], v230
	ds_read_b128 v[164:167], v230 offset:1024
	ds_read_b128 v[168:171], v230 offset:2048
	ds_read_b128 v[172:175], v230 offset:3072
	ds_read_b128 v[176:179], v230 offset:4096
	ds_read_b128 v[180:183], v230 offset:5120
	ds_read_b128 v[204:207], v230 offset:6144
	ds_read_b128 v[208:211], v230 offset:7168
	ds_read_b128 v[212:215], v249
	ds_read_b128 v[232:235], v249 offset:1024
	global_load_lds_dwordx4 v198, s[98:99]
	s_add_i32 m0, s30, 0xe000
	s_nop 0
	global_load_lds_dwordx4 v196, s[98:99]
	s_waitcnt vmcnt(9)
	s_waitcnt lgkmcnt(0)
	s_barrier
	s_setprio 1
	s_waitcnt lgkmcnt(0)
	v_mfma_f32_16x16x32_bf16 v[124:127], v[128:131], v[160:163], v[124:127]
	v_mfma_f32_16x16x32_bf16 v[120:123], v[136:139], v[160:163], v[120:123]
	v_mfma_f32_16x16x32_bf16 v[108:111], v[128:131], v[168:171], v[108:111]
	v_mfma_f32_16x16x32_bf16 v[104:107], v[136:139], v[168:171], v[104:107]
	v_mfma_f32_16x16x32_bf16 v[92:95], v[128:131], v[176:179], v[92:95]
	v_mfma_f32_16x16x32_bf16 v[88:91], v[136:139], v[176:179], v[88:91]
	v_mfma_f32_16x16x32_bf16 v[76:79], v[128:131], v[204:207], v[76:79]
	v_mfma_f32_16x16x32_bf16 v[72:75], v[136:139], v[204:207], v[72:75]
	s_setprio 0
	s_setprio 1
	v_mfma_f32_16x16x32_bf16 v[124:127], v[132:135], v[164:167], v[124:127]
	v_mfma_f32_16x16x32_bf16 v[120:123], v[140:143], v[164:167], v[120:123]
	v_mfma_f32_16x16x32_bf16 v[108:111], v[132:135], v[172:175], v[108:111]
	v_mfma_f32_16x16x32_bf16 v[104:107], v[140:143], v[172:175], v[104:107]
	v_mfma_f32_16x16x32_bf16 v[92:95], v[132:135], v[180:183], v[92:95]
	v_mfma_f32_16x16x32_bf16 v[88:91], v[140:143], v[180:183], v[88:91]
	v_mfma_f32_16x16x32_bf16 v[76:79], v[132:135], v[208:211], v[76:79]
	v_mfma_f32_16x16x32_bf16 v[72:75], v[140:143], v[208:211], v[72:75]
	s_setprio 0
	s_setprio 1
	v_mfma_f32_16x16x32_bf16 v[116:119], v[144:147], v[160:163], v[116:119]
	v_mfma_f32_16x16x32_bf16 v[112:115], v[152:155], v[160:163], v[112:115]
	v_mfma_f32_16x16x32_bf16 v[100:103], v[144:147], v[168:171], v[100:103]
	v_mfma_f32_16x16x32_bf16 v[96:99], v[152:155], v[168:171], v[96:99]
	v_mfma_f32_16x16x32_bf16 v[84:87], v[144:147], v[176:179], v[84:87]
	v_mfma_f32_16x16x32_bf16 v[80:83], v[152:155], v[176:179], v[80:83]
	v_mfma_f32_16x16x32_bf16 v[68:71], v[144:147], v[204:207], v[68:71]
	v_mfma_f32_16x16x32_bf16 v[64:67], v[152:155], v[204:207], v[64:67]
	s_setprio 0
	s_setprio 1
	v_mfma_f32_16x16x32_bf16 v[116:119], v[148:151], v[164:167], v[116:119]
	v_mfma_f32_16x16x32_bf16 v[112:115], v[156:159], v[164:167], v[112:115]
	v_mfma_f32_16x16x32_bf16 v[100:103], v[148:151], v[172:175], v[100:103]
	v_mfma_f32_16x16x32_bf16 v[96:99], v[156:159], v[172:175], v[96:99]
	v_mfma_f32_16x16x32_bf16 v[84:87], v[148:151], v[180:183], v[84:87]
	v_mfma_f32_16x16x32_bf16 v[80:83], v[156:159], v[180:183], v[80:83]
	v_mfma_f32_16x16x32_bf16 v[68:71], v[148:151], v[208:211], v[68:71]
	v_mfma_f32_16x16x32_bf16 v[64:67], v[156:159], v[208:211], v[64:67]
	v_mfma_f32_16x16x32_bf16 v[236:239], v[128:131], v[212:215], v[236:239]
	v_mfma_f32_16x16x32_bf16 v[240:243], v[136:139], v[212:215], v[240:243]
	v_mfma_f32_16x16x32_bf16 v[244:247], v[144:147], v[212:215], v[244:247]
	v_mfma_f32_16x16x32_bf16 v[200:203], v[152:155], v[212:215], v[200:203]
	v_mfma_f32_16x16x32_bf16 v[236:239], v[132:135], v[232:235], v[236:239]
	v_mfma_f32_16x16x32_bf16 v[240:243], v[140:143], v[232:235], v[240:243]
	v_mfma_f32_16x16x32_bf16 v[244:247], v[148:151], v[232:235], v[244:247]
	v_mfma_f32_16x16x32_bf16 v[200:203], v[156:159], v[232:235], v[200:203]
	s_setprio 0
	s_barrier
	s_add_i32 s6, s6, s29
	s_mov_b32 m0, s6
	ds_read_b128 v[160:163], v230 offset:16384
	ds_read_b128 v[164:167], v230 offset:17408
	ds_read_b128 v[168:171], v230 offset:18432
	ds_read_b128 v[172:175], v230 offset:19456
	ds_read_b128 v[176:179], v230 offset:20480
	ds_read_b128 v[180:183], v230 offset:21504
	ds_read_b128 v[204:207], v230 offset:22528
	ds_read_b128 v[208:211], v230 offset:23552
	global_load_lds_dwordx4 v184, s[24:25]
	s_add_i32 m0, s6, 0x2000
	s_add_u32 s22, s24, 0xb0000
	s_addc_u32 s23, s25, 0
	s_add_i32 s6, s51, s29
	global_load_lds_dwordx4 v194, s[24:25]
	s_mov_b32 m0, s6
	s_nop 0
	global_load_lds_dwordx4 v184, s[22:23]
	s_add_i32 m0, s6, 0x2000
	s_nop 0
	global_load_lds_dwordx4 v194, s[22:23]
	s_mov_b32 m0, s30
	s_nop 0
	global_load_lds_dwordx4 v198, s[26:27]
	s_mov_b32 m0, s31
	s_nop 0
	global_load_lds_dwordx4 v196, s[26:27]
	s_and_b32 m0, s30, 0xc00
	s_add_i32 m0, m0, 0x20800
	s_nop 0
	global_load_lds_dwordx4 v248, s[26:27]
	s_waitcnt vmcnt(9)
	s_waitcnt lgkmcnt(0)
	s_barrier
; #define PG8_STAGE(bufoff, gbase, voff) do { _Pragma("unroll") for (int _i = 0; _i < 2; ++_i) \
;         __builtin_amdgcn_global_load_lds((const unsigned*)((const char*)(gbase) + (voff)[_i]), (PG8_LAS unsigned*)(lds + (bufoff) + ldsw + _i * 8192), 16, 0, 0); } while (0)
; #define PG8_LDA(dst, b, h) do { _Pragma("unroll") for (int m = 0; m < 4; ++m) _Pragma("unroll") for (int k = 0; k < 2; ++k) dst[m][k] = *(const PG8_LAS bf16x8*)(lds + PG8_SA(b, h) + aoff + m * 2048 + k * 1024); } while (0)
; #define PG8_LDB(dst, b, h) do { _Pragma("unroll") for (int n = 0; n < 2; ++n) _Pragma("unroll") for (int k = 0; k < 2; ++k) dst[n][k] = *(const PG8_LAS bf16x8*)(lds + PG8_SB(b, h) + boff + n * 2048 + k * 1024); } while (0)
; #define PG8_MMA(ai, bj, At, Bt) do { __builtin_amdgcn_s_setprio(1); _Pragma("unroll") for (int m = 0; m < 4; ++m) _Pragma("unroll") for (int n = 0; n < 2; ++n) _Pragma("unroll") for (int k = 0; k < 2; ++k) \
;         acc[ai][bj][m][n] = __builtin_amdgcn_mfma_f32_16x16x32_bf16(Bt[n][k], At[m][k], acc[ai][bj][m][n], 0, 0, 0); __builtin_amdgcn_s_setprio(0); } while (0)
; #define PG8_WAIT_V(n) asm volatile("s_waitcnt vmcnt(" #n ")" ::: "memory")
; #define PG8_WAIT_L(n) asm volatile("s_waitcnt lgkmcnt(" #n ")" ::: "memory")
; #define PG8_BAR __builtin_amdgcn_s_barrier()
; #define PG8_SCHED __builtin_amdgcn_sched_barrier(0)
; template <class Epi, class Sched, bool ALIGN_EPI = false, bool SP2 = false>
; __device__ __forceinline__ void gemm_phase(PG8_LAS unsigned char* lds, const Gemm g, const Sched& S, const Epi& E) {
;     ...
;             PG8_WAIT_V(8); PG8_WAIT_L(0); PG8_BAR; PG8_MMA(1, 0, At, B0); PG8_MMA(1, 1, At, B1); PG8_BAR; PG8_SCHED;
;             PG8_LDB(B0, 1, 0); PG8_LDB(B1, 1, 1); PG8_SCHED; PG8_LDA(At, 1, 0); PG8_STAGE(PG8_SA(0, 1), a2 + hstep, voffA);
;             PG8_WAIT_V(8); PG8_WAIT_L(0); PG8_BAR; PG8_MMA(0, 0, At, B0); PG8_MMA(0, 1, At, B1); PG8_BAR; PG8_SCHED;
	s_setprio 1
	s_waitcnt lgkmcnt(0)
	v_mfma_f32_16x16x32_bf16 v[60:63], v[128:131], v[160:163], v[60:63]
	v_mfma_f32_16x16x32_bf16 v[56:59], v[136:139], v[160:163], v[56:59]
	v_mfma_f32_16x16x32_bf16 v[44:47], v[128:131], v[168:171], v[44:47]
	v_mfma_f32_16x16x32_bf16 v[40:43], v[136:139], v[168:171], v[40:43]
	v_mfma_f32_16x16x32_bf16 v[28:31], v[128:131], v[176:179], v[28:31]
	v_mfma_f32_16x16x32_bf16 v[24:27], v[136:139], v[176:179], v[24:27]
	v_mfma_f32_16x16x32_bf16 v[12:15], v[128:131], v[204:207], v[12:15]
	v_mfma_f32_16x16x32_bf16 v[8:11], v[136:139], v[204:207], v[8:11]
	s_setprio 0
	s_setprio 1
	v_mfma_f32_16x16x32_bf16 v[60:63], v[132:135], v[164:167], v[60:63]
	v_mfma_f32_16x16x32_bf16 v[56:59], v[140:143], v[164:167], v[56:59]
	v_mfma_f32_16x16x32_bf16 v[44:47], v[132:135], v[172:175], v[44:47]
	v_mfma_f32_16x16x32_bf16 v[40:43], v[140:143], v[172:175], v[40:43]
	v_mfma_f32_16x16x32_bf16 v[28:31], v[132:135], v[180:183], v[28:31]
	v_mfma_f32_16x16x32_bf16 v[24:27], v[140:143], v[180:183], v[24:27]
	v_mfma_f32_16x16x32_bf16 v[12:15], v[132:135], v[208:211], v[12:15]
	v_mfma_f32_16x16x32_bf16 v[8:11], v[140:143], v[208:211], v[8:11]
	s_setprio 0
	s_setprio 1
	v_mfma_f32_16x16x32_bf16 v[52:55], v[144:147], v[160:163], v[52:55]
	v_mfma_f32_16x16x32_bf16 v[48:51], v[152:155], v[160:163], v[48:51]
	v_mfma_f32_16x16x32_bf16 v[36:39], v[144:147], v[168:171], v[36:39]
	v_mfma_f32_16x16x32_bf16 v[32:35], v[152:155], v[168:171], v[32:35]
	v_mfma_f32_16x16x32_bf16 v[20:23], v[144:147], v[176:179], v[20:23]
	v_mfma_f32_16x16x32_bf16 v[16:19], v[152:155], v[176:179], v[16:19]
	v_mfma_f32_16x16x32_bf16 v[4:7], v[144:147], v[204:207], v[4:7]
	v_mfma_f32_16x16x32_bf16 v[0:3], v[152:155], v[204:207], v[0:3]
	s_setprio 0
	s_setprio 1
	v_mfma_f32_16x16x32_bf16 v[52:55], v[148:151], v[164:167], v[52:55]
	v_mfma_f32_16x16x32_bf16 v[48:51], v[156:159], v[164:167], v[48:51]
	v_mfma_f32_16x16x32_bf16 v[36:39], v[148:151], v[172:175], v[36:39]
	v_mfma_f32_16x16x32_bf16 v[32:35], v[156:159], v[172:175], v[32:35]
	v_mfma_f32_16x16x32_bf16 v[20:23], v[148:151], v[180:183], v[20:23]
	v_mfma_f32_16x16x32_bf16 v[16:19], v[156:159], v[180:183], v[16:19]
	v_mfma_f32_16x16x32_bf16 v[4:7], v[148:151], v[208:211], v[4:7]
	v_mfma_f32_16x16x32_bf16 v[0:3], v[156:159], v[208:211], v[0:3]
	s_setprio 0
	s_barrier
	s_add_i32 s6, 0, 0x18000
	s_add_i32 s51, 0, 0x1c000
	v_add_u32_e32 v140, s6, v228
	v_add_u32_e32 v156, s51, v228
	ds_read_b128 v[128:131], v140
	ds_read_b128 v[132:135], v140 offset:1024
	ds_read_b128 v[136:139], v140 offset:2048
	ds_read_b128 v[140:143], v140 offset:3072
	ds_read_b128 v[144:147], v156
	ds_read_b128 v[148:151], v156 offset:1024
	ds_read_b128 v[152:155], v156 offset:2048
	ds_read_b128 v[156:159], v156 offset:3072
	s_add_u32 s22, s26, 0xb0000
	s_addc_u32 s23, s27, 0
	s_mov_b32 m0, s34
	ds_read_b128 v[160:163], v230 offset:32768
	ds_read_b128 v[164:167], v230 offset:33792
	ds_read_b128 v[168:171], v230 offset:34816
	ds_read_b128 v[172:175], v230 offset:35840
	ds_read_b128 v[176:179], v230 offset:36864
	ds_read_b128 v[180:183], v230 offset:37888
	ds_read_b128 v[204:207], v230 offset:38912
	ds_read_b128 v[208:211], v230 offset:39936
	ds_read_b128 v[212:215], v249 offset:4096
	ds_read_b128 v[232:235], v249 offset:5120
	global_load_lds_dwordx4 v198, s[22:23]
	s_mov_b32 m0, s40
	s_nop 0
	global_load_lds_dwordx4 v196, s[22:23]
	s_waitcnt vmcnt(9)
	s_waitcnt lgkmcnt(0)
	s_barrier
	s_setprio 1
	s_waitcnt lgkmcnt(0)
	v_mfma_f32_16x16x32_bf16 v[124:127], v[128:131], v[160:163], v[124:127]
	v_mfma_f32_16x16x32_bf16 v[120:123], v[136:139], v[160:163], v[120:123]
	v_mfma_f32_16x16x32_bf16 v[108:111], v[128:131], v[168:171], v[108:111]
	v_mfma_f32_16x16x32_bf16 v[104:107], v[136:139], v[168:171], v[104:107]
	v_mfma_f32_16x16x32_bf16 v[92:95], v[128:131], v[176:179], v[92:95]
	v_mfma_f32_16x16x32_bf16 v[88:91], v[136:139], v[176:179], v[88:91]
	v_mfma_f32_16x16x32_bf16 v[76:79], v[128:131], v[204:207], v[76:79]
	v_mfma_f32_16x16x32_bf16 v[72:75], v[136:139], v[204:207], v[72:75]
	s_setprio 0
	s_setprio 1
	v_mfma_f32_16x16x32_bf16 v[124:127], v[132:135], v[164:167], v[124:127]
	v_mfma_f32_16x16x32_bf16 v[120:123], v[140:143], v[164:167], v[120:123]
	v_mfma_f32_16x16x32_bf16 v[108:111], v[132:135], v[172:175], v[108:111]
	v_mfma_f32_16x16x32_bf16 v[104:107], v[140:143], v[172:175], v[104:107]
	v_mfma_f32_16x16x32_bf16 v[92:95], v[132:135], v[180:183], v[92:95]
	v_mfma_f32_16x16x32_bf16 v[88:91], v[140:143], v[180:183], v[88:91]
	v_mfma_f32_16x16x32_bf16 v[76:79], v[132:135], v[208:211], v[76:79]
	v_mfma_f32_16x16x32_bf16 v[72:75], v[140:143], v[208:211], v[72:75]
	s_setprio 0
	s_setprio 1
	v_mfma_f32_16x16x32_bf16 v[116:119], v[144:147], v[160:163], v[116:119]
	v_mfma_f32_16x16x32_bf16 v[112:115], v[152:155], v[160:163], v[112:115]
	v_mfma_f32_16x16x32_bf16 v[100:103], v[144:147], v[168:171], v[100:103]
	v_mfma_f32_16x16x32_bf16 v[96:99], v[152:155], v[168:171], v[96:99]
	v_mfma_f32_16x16x32_bf16 v[84:87], v[144:147], v[176:179], v[84:87]
	v_mfma_f32_16x16x32_bf16 v[80:83], v[152:155], v[176:179], v[80:83]
	v_mfma_f32_16x16x32_bf16 v[68:71], v[144:147], v[204:207], v[68:71]
	v_mfma_f32_16x16x32_bf16 v[64:67], v[152:155], v[204:207], v[64:67]
	s_setprio 0
	s_setprio 1
	v_mfma_f32_16x16x32_bf16 v[116:119], v[148:151], v[164:167], v[116:119]
	v_mfma_f32_16x16x32_bf16 v[112:115], v[156:159], v[164:167], v[112:115]
	v_mfma_f32_16x16x32_bf16 v[100:103], v[148:151], v[172:175], v[100:103]
	v_mfma_f32_16x16x32_bf16 v[96:99], v[156:159], v[172:175], v[96:99]
	v_mfma_f32_16x16x32_bf16 v[84:87], v[148:151], v[180:183], v[84:87]
	v_mfma_f32_16x16x32_bf16 v[80:83], v[156:159], v[180:183], v[80:83]
	v_mfma_f32_16x16x32_bf16 v[68:71], v[148:151], v[208:211], v[68:71]
	v_mfma_f32_16x16x32_bf16 v[64:67], v[156:159], v[208:211], v[64:67]
	v_mfma_f32_16x16x32_bf16 v[236:239], v[128:131], v[212:215], v[236:239]
	v_mfma_f32_16x16x32_bf16 v[240:243], v[136:139], v[212:215], v[240:243]
	v_mfma_f32_16x16x32_bf16 v[244:247], v[144:147], v[212:215], v[244:247]
	v_mfma_f32_16x16x32_bf16 v[200:203], v[152:155], v[212:215], v[200:203]
	v_mfma_f32_16x16x32_bf16 v[236:239], v[132:135], v[232:235], v[236:239]
	v_mfma_f32_16x16x32_bf16 v[240:243], v[140:143], v[232:235], v[240:243]
	v_mfma_f32_16x16x32_bf16 v[244:247], v[148:151], v[232:235], v[244:247]
	v_mfma_f32_16x16x32_bf16 v[200:203], v[156:159], v[232:235], v[200:203]
	s_setprio 0
	s_barrier
; #define PG8_STAGE(bufoff, gbase, voff) do { _Pragma("unroll") for (int _i = 0; _i < 2; ++_i) \
;         __builtin_amdgcn_global_load_lds((const unsigned*)((const char*)(gbase) + (voff)[_i]), (PG8_LAS unsigned*)(lds + (bufoff) + ldsw + _i * 8192), 16, 0, 0); } while (0)
; #define PG8_LDA(dst, b, h) do { _Pragma("unroll") for (int m = 0; m < 4; ++m) _Pragma("unroll") for (int k = 0; k < 2; ++k) dst[m][k] = *(const PG8_LAS bf16x8*)(lds + PG8_SA(b, h) + aoff + m * 2048 + k * 1024); } while (0)
; #define PG8_MMA(ai, bj, At, Bt) do { __builtin_amdgcn_s_setprio(1); _Pragma("unroll") for (int m = 0; m < 4; ++m) _Pragma("unroll") for (int n = 0; n < 2; ++n) _Pragma("unroll") for (int k = 0; k < 2; ++k) \
;         acc[ai][bj][m][n] = __builtin_amdgcn_mfma_f32_16x16x32_bf16(Bt[n][k], At[m][k], acc[ai][bj][m][n], 0, 0, 0); __builtin_amdgcn_s_setprio(0); } while (0)
; #define PG8_WAIT_V(n) asm volatile("s_waitcnt vmcnt(" #n ")" ::: "memory")
; #define PG8_WAIT_L(n) asm volatile("s_waitcnt lgkmcnt(" #n ")" ::: "memory")
; #define PG8_BAR __builtin_amdgcn_s_barrier()
; #define PG8_SCHED __builtin_amdgcn_sched_barrier(0)
; template <class Epi, class Sched, bool ALIGN_EPI = false, bool SP2 = false>
; __device__ __forceinline__ void gemm_phase(PG8_LAS unsigned char* lds, const Gemm g, const Sched& S, const Epi& E) {
;     ...
;             PG8_LDA(At, 1, 1); PG8_STAGE(PG8_SB(1, 0), b3, voffB); PG8_STAGE(PG8_SB(1, 1), b3 + hstep, voffB); PG8_STAGE(PG8_SA(1, 0), a3, voffA);
;             PG8_WAIT_V(8); PG8_WAIT_L(0); PG8_BAR; PG8_MMA(1, 0, At, B0); PG8_MMA(1, 1, At, B1); PG8_BAR; PG8_SCHED;
	s_add_i32 s22, s6, s29
	s_add_u32 s98, s24, 0x80
	s_addc_u32 s99, s25, 0
	s_mov_b32 m0, s22
	ds_read_b128 v[160:163], v230 offset:49152
	ds_read_b128 v[164:167], v230 offset:50176
	ds_read_b128 v[168:171], v230 offset:51200
	ds_read_b128 v[172:175], v230 offset:52224
	ds_read_b128 v[176:179], v230 offset:53248
	ds_read_b128 v[180:183], v230 offset:54272
	ds_read_b128 v[204:207], v230 offset:55296
	ds_read_b128 v[208:211], v230 offset:56320
	global_load_lds_dwordx4 v184, s[98:99]
	s_add_i32 m0, s22, 0x2000
	s_add_u32 s100, s24, 0xb0080
	s_addc_u32 s101, s25, 0
	s_add_i32 s22, s51, s29
	global_load_lds_dwordx4 v194, s[98:99]
	s_mov_b32 m0, s22
	s_add_u32 s98, s26, 0x80
	s_addc_u32 s99, s27, 0
	global_load_lds_dwordx4 v184, s[100:101]
	s_add_i32 m0, s22, 0x2000
	s_nop 0
	global_load_lds_dwordx4 v194, s[100:101]
	s_mov_b32 m0, s41
	s_nop 0
	global_load_lds_dwordx4 v198, s[98:99]
	s_mov_b32 m0, s42
	s_nop 0
	global_load_lds_dwordx4 v196, s[98:99]
	s_and_b32 m0, s30, 0xc00
	s_add_i32 m0, m0, 0x21800
	s_nop 0
	global_load_lds_dwordx4 v248, s[98:99]
	s_waitcnt vmcnt(9)
	s_waitcnt lgkmcnt(0)
	s_barrier
	s_setprio 1
	s_waitcnt lgkmcnt(0)
	v_mfma_f32_16x16x32_bf16 v[60:63], v[128:131], v[160:163], v[60:63]
	v_mfma_f32_16x16x32_bf16 v[56:59], v[136:139], v[160:163], v[56:59]
	v_mfma_f32_16x16x32_bf16 v[44:47], v[128:131], v[168:171], v[44:47]
	v_mfma_f32_16x16x32_bf16 v[40:43], v[136:139], v[168:171], v[40:43]
	v_mfma_f32_16x16x32_bf16 v[28:31], v[128:131], v[176:179], v[28:31]
	v_mfma_f32_16x16x32_bf16 v[24:27], v[136:139], v[176:179], v[24:27]
	v_mfma_f32_16x16x32_bf16 v[12:15], v[128:131], v[204:207], v[12:15]
	v_mfma_f32_16x16x32_bf16 v[8:11], v[136:139], v[204:207], v[8:11]
	s_setprio 0
	s_setprio 1
	v_mfma_f32_16x16x32_bf16 v[60:63], v[132:135], v[164:167], v[60:63]
	v_mfma_f32_16x16x32_bf16 v[56:59], v[140:143], v[164:167], v[56:59]
	v_mfma_f32_16x16x32_bf16 v[44:47], v[132:135], v[172:175], v[44:47]
	v_mfma_f32_16x16x32_bf16 v[40:43], v[140:143], v[172:175], v[40:43]
	v_mfma_f32_16x16x32_bf16 v[28:31], v[132:135], v[180:183], v[28:31]
	v_mfma_f32_16x16x32_bf16 v[24:27], v[140:143], v[180:183], v[24:27]
	v_mfma_f32_16x16x32_bf16 v[12:15], v[132:135], v[208:211], v[12:15]
	v_mfma_f32_16x16x32_bf16 v[8:11], v[140:143], v[208:211], v[8:11]
	s_setprio 0
	s_setprio 1
	v_mfma_f32_16x16x32_bf16 v[52:55], v[144:147], v[160:163], v[52:55]
	v_mfma_f32_16x16x32_bf16 v[48:51], v[152:155], v[160:163], v[48:51]
	v_mfma_f32_16x16x32_bf16 v[36:39], v[144:147], v[168:171], v[36:39]
	v_mfma_f32_16x16x32_bf16 v[32:35], v[152:155], v[168:171], v[32:35]
	v_mfma_f32_16x16x32_bf16 v[20:23], v[144:147], v[176:179], v[20:23]
	v_mfma_f32_16x16x32_bf16 v[16:19], v[152:155], v[176:179], v[16:19]
	v_mfma_f32_16x16x32_bf16 v[4:7], v[144:147], v[204:207], v[4:7]
	v_mfma_f32_16x16x32_bf16 v[0:3], v[152:155], v[204:207], v[0:3]
	s_setprio 0
	s_setprio 1
	v_mfma_f32_16x16x32_bf16 v[52:55], v[148:151], v[164:167], v[52:55]
	v_mfma_f32_16x16x32_bf16 v[48:51], v[156:159], v[164:167], v[48:51]
	v_mfma_f32_16x16x32_bf16 v[36:39], v[148:151], v[172:175], v[36:39]
	v_mfma_f32_16x16x32_bf16 v[32:35], v[156:159], v[172:175], v[32:35]
	v_mfma_f32_16x16x32_bf16 v[20:23], v[148:151], v[180:183], v[20:23]
	v_mfma_f32_16x16x32_bf16 v[16:19], v[156:159], v[180:183], v[16:19]
	v_mfma_f32_16x16x32_bf16 v[4:7], v[148:151], v[208:211], v[4:7]
	v_mfma_f32_16x16x32_bf16 v[0:3], v[156:159], v[208:211], v[0:3]
	s_setprio 0
	s_barrier
	s_add_i32 s50, s50, 2
	s_add_u32 s4, s4, 0x100
	s_addc_u32 s5, s5, 0
	s_cmp_gt_u32 s50, 41
	s_mov_b64 s[22:23], s[0:1]
	s_cbranch_scc0 .LBB0_461
	s_and_b64 vcc, exec, s[16:17]
	s_cbranch_vccz .LBB0_464
	s_barrier

; #define PG8_STAGE(bufoff, gbase, voff) do { _Pragma("unroll") for (int _i = 0; _i < 2; ++_i) \
;         __builtin_amdgcn_global_load_lds((const unsigned*)((const char*)(gbase) + (voff)[_i]), (PG8_LAS unsigned*)(lds + (bufoff) + ldsw + _i * 8192), 16, 0, 0); } while (0)
; #define PG8_LDA(dst, b, h) do { _Pragma("unroll") for (int m = 0; m < 4; ++m) _Pragma("unroll") for (int k = 0; k < 2; ++k) dst[m][k] = *(const PG8_LAS bf16x8*)(lds + PG8_SA(b, h) + aoff + m * 2048 + k * 1024); } while (0)
; #define PG8_LDB(dst, b, h) do { _Pragma("unroll") for (int n = 0; n < 2; ++n) _Pragma("unroll") for (int k = 0; k < 2; ++k) dst[n][k] = *(const PG8_LAS bf16x8*)(lds + PG8_SB(b, h) + boff + n * 2048 + k * 1024); } while (0)
; #define PG8_MMA(ai, bj, At, Bt) do { __builtin_amdgcn_s_setprio(1); _Pragma("unroll") for (int m = 0; m < 4; ++m) _Pragma("unroll") for (int n = 0; n < 2; ++n) _Pragma("unroll") for (int k = 0; k < 2; ++k) \
;         acc[ai][bj][m][n] = __builtin_amdgcn_mfma_f32_16x16x32_bf16(Bt[n][k], At[m][k], acc[ai][bj][m][n], 0, 0, 0); __builtin_amdgcn_s_setprio(0); } while (0)
; #define PG8_BAR __builtin_amdgcn_s_barrier()
; template <class Epi, class Sched, bool ALIGN_EPI = false, bool SP2 = false>
; __device__ __forceinline__ void gemm_phase(PG8_LAS unsigned char* lds, const Gemm g, const Sched& S, const Epi& E) {
;     ...
;         const bool has_next = S.next(ui + 1, nxt);
;         const char* nA = has_next ? (const char*)g.A + (size_t)nxt.pm * tstep : cA; const char* nB = has_next ? (const char*)g.Bt + (size_t)nxt.pn * tstep : cB;
;         for (int t = 0; t < nt; t += 2) {
;             const bool last = (t == nt - 2);
;             const char* a1 = cA + (size_t)(t + 1) * kstep;
;             const char* a2 = last ? nA : cA + (size_t)(t + 2) * kstep; const char* b2 = last ? nB : cB + (size_t)(t + 2) * kstep;
;             const char* a3 = a2 + kstep; const char* b3 = b2 + kstep;
;             if (last && has_next) S.a_ready(nxt);
;             if constexpr (SP2) {
;             PG8_LDB(B0, 0, 0); PG8_LDB(B1, 0, 1); PG8_SCHED; PG8_LDA(At, 0, 0); PG8_STAGE(PG8_SA(1, 1), a1 + hstep, voffA);
;             PG8_WAIT_V(8); PG8_WAIT_L(0); PG8_BAR; PG8_MMA(0, 0, At, B0); PG8_MMA(0, 1, At, B1); PG8_BAR; PG8_SCHED;
;             PG8_LDA(At, 0, 1); PG8_STAGE(PG8_SB(0, 0), b2, voffB); PG8_STAGE(PG8_SB(0, 1), b2 + hstep, voffB); PG8_STAGE(PG8_SA(0, 0), a2, voffA);
.LBB0_509:
	s_add_u32 s2, s0, 0xfffc0080
	s_addc_u32 s3, s1, -1
	s_add_i32 s41, 0, 0x10000
	s_cmp_eq_u32 s40, 12
	s_cselect_b32 s9, s4, s3
	s_cselect_b32 s8, s5, s2
	v_add_u32_e32 v155, s41, v147
	s_cselect_b32 s3, s11, s39
	s_cselect_b32 s2, s24, s25
	s_add_i32 s46, 0, 0x14000
	ds_read_b128 v[128:131], v155
	ds_read_b128 v[132:135], v155 offset:1024
	ds_read_b128 v[156:159], v155 offset:2048
	ds_read_b128 v[170:173], v155 offset:3072
	v_add_u32_e32 v155, s46, v147
	ds_read_b128 v[174:177], v155
	ds_read_b128 v[178:181], v155 offset:1024
	ds_read_b128 v[194:197], v155 offset:2048
	ds_read_b128 v[198:201], v155 offset:3072
	v_lshl_add_u64 v[160:161], s[0:1], 0, v[150:151]
	s_add_i32 m0, s27, 0xc000
	ds_read_b128 v[202:205], v168
	ds_read_b128 v[206:209], v168 offset:1024
	ds_read_b128 v[210:213], v168 offset:2048
	ds_read_b128 v[228:231], v168 offset:3072
	ds_read_b128 v[232:235], v168 offset:4096
	ds_read_b128 v[236:239], v168 offset:5120
	ds_read_b128 v[240:243], v168 offset:6144
	ds_read_b128 v[244:247], v168 offset:7168
	global_load_lds_dwordx4 v[160:161], off
	v_lshl_add_u64 v[160:161], s[0:1], 0, v[152:153]
	s_add_i32 m0, s27, 0xe000
	s_nop 0
	global_load_lds_dwordx4 v[160:161], off
	s_waitcnt vmcnt(8)
	s_waitcnt lgkmcnt(0)
	s_barrier
	s_setprio 1
	s_waitcnt lgkmcnt(0)
	v_mfma_f32_16x16x32_bf16 v[124:127], v[128:131], v[202:205], v[124:127]
	v_mfma_f32_16x16x32_bf16 v[120:123], v[156:159], v[202:205], v[120:123]
	v_mfma_f32_16x16x32_bf16 v[108:111], v[128:131], v[210:213], v[108:111]
	v_mfma_f32_16x16x32_bf16 v[104:107], v[156:159], v[210:213], v[104:107]
	v_mfma_f32_16x16x32_bf16 v[92:95], v[128:131], v[232:235], v[92:95]
	v_mfma_f32_16x16x32_bf16 v[88:91], v[156:159], v[232:235], v[88:91]
	v_mfma_f32_16x16x32_bf16 v[76:79], v[128:131], v[240:243], v[76:79]
	v_mfma_f32_16x16x32_bf16 v[72:75], v[156:159], v[240:243], v[72:75]
	s_setprio 0
	s_setprio 1
	v_mfma_f32_16x16x32_bf16 v[124:127], v[132:135], v[206:209], v[124:127]
	v_mfma_f32_16x16x32_bf16 v[120:123], v[170:173], v[206:209], v[120:123]
	v_mfma_f32_16x16x32_bf16 v[108:111], v[132:135], v[228:231], v[108:111]
	v_mfma_f32_16x16x32_bf16 v[104:107], v[170:173], v[228:231], v[104:107]
	v_mfma_f32_16x16x32_bf16 v[92:95], v[132:135], v[236:239], v[92:95]
	v_mfma_f32_16x16x32_bf16 v[88:91], v[170:173], v[236:239], v[88:91]
	v_mfma_f32_16x16x32_bf16 v[76:79], v[132:135], v[244:247], v[76:79]
	v_mfma_f32_16x16x32_bf16 v[72:75], v[170:173], v[244:247], v[72:75]
	s_setprio 0
	s_setprio 1
	v_mfma_f32_16x16x32_bf16 v[116:119], v[174:177], v[202:205], v[116:119]
	v_mfma_f32_16x16x32_bf16 v[112:115], v[194:197], v[202:205], v[112:115]
	v_mfma_f32_16x16x32_bf16 v[100:103], v[174:177], v[210:213], v[100:103]
	v_mfma_f32_16x16x32_bf16 v[96:99], v[194:197], v[210:213], v[96:99]
	v_mfma_f32_16x16x32_bf16 v[84:87], v[174:177], v[232:235], v[84:87]
	v_mfma_f32_16x16x32_bf16 v[80:83], v[194:197], v[232:235], v[80:83]
	v_mfma_f32_16x16x32_bf16 v[68:71], v[174:177], v[240:243], v[68:71]
	v_mfma_f32_16x16x32_bf16 v[64:67], v[194:197], v[240:243], v[64:67]
	s_setprio 0
	s_setprio 1
	v_mfma_f32_16x16x32_bf16 v[116:119], v[178:181], v[206:209], v[116:119]
	v_mfma_f32_16x16x32_bf16 v[112:115], v[198:201], v[206:209], v[112:115]
	v_mfma_f32_16x16x32_bf16 v[100:103], v[178:181], v[228:231], v[100:103]
	v_mfma_f32_16x16x32_bf16 v[96:99], v[198:201], v[228:231], v[96:99]
	v_mfma_f32_16x16x32_bf16 v[84:87], v[178:181], v[236:239], v[84:87]
	v_mfma_f32_16x16x32_bf16 v[80:83], v[198:201], v[236:239], v[80:83]
	v_mfma_f32_16x16x32_bf16 v[68:71], v[178:181], v[244:247], v[68:71]
	v_mfma_f32_16x16x32_bf16 v[64:67], v[198:201], v[244:247], v[64:67]
	s_setprio 0
	s_barrier
	s_add_i32 s41, s41, s26
	v_lshl_add_u64 v[160:161], s[2:3], 0, v[140:141]
	s_mov_b32 m0, s41
	ds_read_b128 v[202:205], v168 offset:16384
	ds_read_b128 v[206:209], v168 offset:17408
	ds_read_b128 v[210:213], v168 offset:18432
	ds_read_b128 v[228:231], v168 offset:19456
	ds_read_b128 v[232:235], v168 offset:20480
	ds_read_b128 v[236:239], v168 offset:21504
	ds_read_b128 v[240:243], v168 offset:22528
	ds_read_b128 v[244:247], v168 offset:23552
	global_load_lds_dwordx4 v[160:161], off
	s_add_i32 m0, s41, 0x2000
	s_add_u32 s44, s2, 0x40000
	v_lshl_add_u64 v[182:183], s[2:3], 0, v[136:137]
	s_addc_u32 s45, s3, 0
	s_add_i32 s41, s46, s26
	global_load_lds_dwordx4 v[182:183], off
	v_lshl_add_u64 v[214:215], s[44:45], 0, v[140:141]
	s_mov_b32 m0, s41
	v_lshl_add_u64 v[248:249], s[8:9], 0, v[138:139]
	global_load_lds_dwordx4 v[214:215], off
	v_lshl_add_u64 v[214:215], s[44:45], 0, v[136:137]
	s_add_i32 m0, s41, 0x2000
	s_nop 0
	global_load_lds_dwordx4 v[214:215], off
	v_lshl_add_u64 v[214:215], s[8:9], 0, v[142:143]
	s_mov_b32 m0, s27
	s_nop 0
	global_load_lds_dwordx4 v[214:215], off
	s_mov_b32 m0, s28
	s_nop 0
	global_load_lds_dwordx4 v[248:249], off
	s_waitcnt vmcnt(8)
	s_waitcnt lgkmcnt(0)
	s_barrier
; #define PG8_STAGE(bufoff, gbase, voff) do { _Pragma("unroll") for (int _i = 0; _i < 2; ++_i) \
;         __builtin_amdgcn_global_load_lds((const unsigned*)((const char*)(gbase) + (voff)[_i]), (PG8_LAS unsigned*)(lds + (bufoff) + ldsw + _i * 8192), 16, 0, 0); } while (0)
; #define PG8_LDA(dst, b, h) do { _Pragma("unroll") for (int m = 0; m < 4; ++m) _Pragma("unroll") for (int k = 0; k < 2; ++k) dst[m][k] = *(const PG8_LAS bf16x8*)(lds + PG8_SA(b, h) + aoff + m * 2048 + k * 1024); } while (0)
; #define PG8_LDB(dst, b, h) do { _Pragma("unroll") for (int n = 0; n < 2; ++n) _Pragma("unroll") for (int k = 0; k < 2; ++k) dst[n][k] = *(const PG8_LAS bf16x8*)(lds + PG8_SB(b, h) + boff + n * 2048 + k * 1024); } while (0)
; #define PG8_MMA(ai, bj, At, Bt) do { __builtin_amdgcn_s_setprio(1); _Pragma("unroll") for (int m = 0; m < 4; ++m) _Pragma("unroll") for (int n = 0; n < 2; ++n) _Pragma("unroll") for (int k = 0; k < 2; ++k) \
;         acc[ai][bj][m][n] = __builtin_amdgcn_mfma_f32_16x16x32_bf16(Bt[n][k], At[m][k], acc[ai][bj][m][n], 0, 0, 0); __builtin_amdgcn_s_setprio(0); } while (0)
; #define PG8_WAIT_V(n) asm volatile("s_waitcnt vmcnt(" #n ")" ::: "memory")
; #define PG8_WAIT_L(n) asm volatile("s_waitcnt lgkmcnt(" #n ")" ::: "memory")
; #define PG8_BAR __builtin_amdgcn_s_barrier()
; #define PG8_SCHED __builtin_amdgcn_sched_barrier(0)
; template <class Epi, class Sched, bool ALIGN_EPI = false, bool SP2 = false>
; __device__ __forceinline__ void gemm_phase(PG8_LAS unsigned char* lds, const Gemm g, const Sched& S, const Epi& E) {
;     ...
;             PG8_WAIT_V(8); PG8_WAIT_L(0); PG8_BAR; PG8_MMA(1, 0, At, B0); PG8_MMA(1, 1, At, B1); PG8_BAR; PG8_SCHED;
;             PG8_LDB(B0, 1, 0); PG8_LDB(B1, 1, 1); PG8_SCHED; PG8_LDA(At, 1, 0); PG8_STAGE(PG8_SA(0, 1), a2 + hstep, voffA);
;             PG8_WAIT_V(8); PG8_WAIT_L(0); PG8_BAR; PG8_MMA(0, 0, At, B0); PG8_MMA(0, 1, At, B1); PG8_BAR; PG8_SCHED;
	s_setprio 1
	s_waitcnt lgkmcnt(0)
	v_mfma_f32_16x16x32_bf16 v[60:63], v[128:131], v[202:205], v[60:63]
	v_mfma_f32_16x16x32_bf16 v[56:59], v[156:159], v[202:205], v[56:59]
	v_mfma_f32_16x16x32_bf16 v[44:47], v[128:131], v[210:213], v[44:47]
	v_mfma_f32_16x16x32_bf16 v[40:43], v[156:159], v[210:213], v[40:43]
	v_mfma_f32_16x16x32_bf16 v[28:31], v[128:131], v[232:235], v[28:31]
	v_mfma_f32_16x16x32_bf16 v[24:27], v[156:159], v[232:235], v[24:27]
	v_mfma_f32_16x16x32_bf16 v[12:15], v[128:131], v[240:243], v[12:15]
	v_mfma_f32_16x16x32_bf16 v[8:11], v[156:159], v[240:243], v[8:11]
	s_setprio 0
	s_setprio 1
	v_mfma_f32_16x16x32_bf16 v[60:63], v[132:135], v[206:209], v[60:63]
	v_mfma_f32_16x16x32_bf16 v[56:59], v[170:173], v[206:209], v[56:59]
	v_mfma_f32_16x16x32_bf16 v[44:47], v[132:135], v[228:231], v[44:47]
	v_mfma_f32_16x16x32_bf16 v[40:43], v[170:173], v[228:231], v[40:43]
	v_mfma_f32_16x16x32_bf16 v[28:31], v[132:135], v[236:239], v[28:31]
	v_mfma_f32_16x16x32_bf16 v[24:27], v[170:173], v[236:239], v[24:27]
	v_mfma_f32_16x16x32_bf16 v[12:15], v[132:135], v[244:247], v[12:15]
	v_mfma_f32_16x16x32_bf16 v[8:11], v[170:173], v[244:247], v[8:11]
	s_setprio 0
	s_setprio 1
	v_mfma_f32_16x16x32_bf16 v[52:55], v[174:177], v[202:205], v[52:55]
	v_mfma_f32_16x16x32_bf16 v[48:51], v[194:197], v[202:205], v[48:51]
	v_mfma_f32_16x16x32_bf16 v[36:39], v[174:177], v[210:213], v[36:39]
	v_mfma_f32_16x16x32_bf16 v[32:35], v[194:197], v[210:213], v[32:35]
	v_mfma_f32_16x16x32_bf16 v[20:23], v[174:177], v[232:235], v[20:23]
	v_mfma_f32_16x16x32_bf16 v[16:19], v[194:197], v[232:235], v[16:19]
	v_mfma_f32_16x16x32_bf16 v[4:7], v[174:177], v[240:243], v[4:7]
	v_mfma_f32_16x16x32_bf16 v[0:3], v[194:197], v[240:243], v[0:3]
	s_setprio 0
	s_setprio 1
	v_mfma_f32_16x16x32_bf16 v[52:55], v[178:181], v[206:209], v[52:55]
	v_mfma_f32_16x16x32_bf16 v[48:51], v[198:201], v[206:209], v[48:51]
	v_mfma_f32_16x16x32_bf16 v[36:39], v[178:181], v[228:231], v[36:39]
	v_mfma_f32_16x16x32_bf16 v[32:35], v[198:201], v[228:231], v[32:35]
	v_mfma_f32_16x16x32_bf16 v[20:23], v[178:181], v[236:239], v[20:23]
	v_mfma_f32_16x16x32_bf16 v[16:19], v[198:201], v[236:239], v[16:19]
	v_mfma_f32_16x16x32_bf16 v[4:7], v[178:181], v[244:247], v[4:7]
	v_mfma_f32_16x16x32_bf16 v[0:3], v[198:201], v[244:247], v[0:3]
	s_setprio 0
	s_barrier
	s_add_i32 s41, 0, 0x18000
	v_add_u32_e32 v155, s41, v147
	s_add_i32 s44, 0, 0x1c000
	ds_read_b128 v[128:131], v155
	ds_read_b128 v[132:135], v155 offset:1024
	ds_read_b128 v[156:159], v155 offset:2048
	ds_read_b128 v[170:173], v155 offset:3072
	v_add_u32_e32 v155, s44, v147
	ds_read_b128 v[174:177], v155
	ds_read_b128 v[178:181], v155 offset:1024
	ds_read_b128 v[194:197], v155 offset:2048
	ds_read_b128 v[198:201], v155 offset:3072
	s_add_u32 s8, s8, 0x40000
	s_addc_u32 s9, s9, 0
	s_mov_b32 m0, s29
	v_lshl_add_u64 v[224:225], s[8:9], 0, v[142:143]
	ds_read_b128 v[202:205], v168 offset:32768
	ds_read_b128 v[206:209], v168 offset:33792
	ds_read_b128 v[210:213], v168 offset:34816
	ds_read_b128 v[228:231], v168 offset:35840
	ds_read_b128 v[232:235], v168 offset:36864
	ds_read_b128 v[236:239], v168 offset:37888
	ds_read_b128 v[240:243], v168 offset:38912
	ds_read_b128 v[244:247], v168 offset:39936
	global_load_lds_dwordx4 v[224:225], off
	v_lshl_add_u64 v[224:225], s[8:9], 0, v[138:139]
	s_mov_b32 m0, s30
	s_nop 0
	global_load_lds_dwordx4 v[224:225], off
	s_waitcnt vmcnt(8)
	s_waitcnt lgkmcnt(0)
	s_barrier
	s_setprio 1
	s_waitcnt lgkmcnt(0)
	v_mfma_f32_16x16x32_bf16 v[124:127], v[128:131], v[202:205], v[124:127]
	v_mfma_f32_16x16x32_bf16 v[120:123], v[156:159], v[202:205], v[120:123]
	v_mfma_f32_16x16x32_bf16 v[108:111], v[128:131], v[210:213], v[108:111]
	v_mfma_f32_16x16x32_bf16 v[104:107], v[156:159], v[210:213], v[104:107]
	v_mfma_f32_16x16x32_bf16 v[92:95], v[128:131], v[232:235], v[92:95]
	v_mfma_f32_16x16x32_bf16 v[88:91], v[156:159], v[232:235], v[88:91]
	v_mfma_f32_16x16x32_bf16 v[76:79], v[128:131], v[240:243], v[76:79]
	v_mfma_f32_16x16x32_bf16 v[72:75], v[156:159], v[240:243], v[72:75]
	s_setprio 0
	s_setprio 1
	v_mfma_f32_16x16x32_bf16 v[124:127], v[132:135], v[206:209], v[124:127]
	v_mfma_f32_16x16x32_bf16 v[120:123], v[170:173], v[206:209], v[120:123]
	v_mfma_f32_16x16x32_bf16 v[108:111], v[132:135], v[228:231], v[108:111]
	v_mfma_f32_16x16x32_bf16 v[104:107], v[170:173], v[228:231], v[104:107]
	v_mfma_f32_16x16x32_bf16 v[92:95], v[132:135], v[236:239], v[92:95]
	v_mfma_f32_16x16x32_bf16 v[88:91], v[170:173], v[236:239], v[88:91]
	v_mfma_f32_16x16x32_bf16 v[76:79], v[132:135], v[244:247], v[76:79]
	v_mfma_f32_16x16x32_bf16 v[72:75], v[170:173], v[244:247], v[72:75]
	s_setprio 0
	s_setprio 1
	v_mfma_f32_16x16x32_bf16 v[116:119], v[174:177], v[202:205], v[116:119]
	v_mfma_f32_16x16x32_bf16 v[112:115], v[194:197], v[202:205], v[112:115]
	v_mfma_f32_16x16x32_bf16 v[100:103], v[174:177], v[210:213], v[100:103]
	v_mfma_f32_16x16x32_bf16 v[96:99], v[194:197], v[210:213], v[96:99]
	v_mfma_f32_16x16x32_bf16 v[84:87], v[174:177], v[232:235], v[84:87]
	v_mfma_f32_16x16x32_bf16 v[80:83], v[194:197], v[232:235], v[80:83]
	v_mfma_f32_16x16x32_bf16 v[68:71], v[174:177], v[240:243], v[68:71]
	v_mfma_f32_16x16x32_bf16 v[64:67], v[194:197], v[240:243], v[64:67]
	s_setprio 0
	s_setprio 1
	v_mfma_f32_16x16x32_bf16 v[116:119], v[178:181], v[206:209], v[116:119]
	v_mfma_f32_16x16x32_bf16 v[112:115], v[198:201], v[206:209], v[112:115]
	v_mfma_f32_16x16x32_bf16 v[100:103], v[178:181], v[228:231], v[100:103]
	v_mfma_f32_16x16x32_bf16 v[96:99], v[198:201], v[228:231], v[96:99]
	v_mfma_f32_16x16x32_bf16 v[84:87], v[178:181], v[236:239], v[84:87]
	v_mfma_f32_16x16x32_bf16 v[80:83], v[198:201], v[236:239], v[80:83]
	v_mfma_f32_16x16x32_bf16 v[68:71], v[178:181], v[244:247], v[68:71]
	v_mfma_f32_16x16x32_bf16 v[64:67], v[198:201], v[244:247], v[64:67]
	s_setprio 0
	s_barrier
; #define PG8_STAGE(bufoff, gbase, voff) do { _Pragma("unroll") for (int _i = 0; _i < 2; ++_i) \
;         __builtin_amdgcn_global_load_lds((const unsigned*)((const char*)(gbase) + (voff)[_i]), (PG8_LAS unsigned*)(lds + (bufoff) + ldsw + _i * 8192), 16, 0, 0); } while (0)
; #define PG8_LDA(dst, b, h) do { _Pragma("unroll") for (int m = 0; m < 4; ++m) _Pragma("unroll") for (int k = 0; k < 2; ++k) dst[m][k] = *(const PG8_LAS bf16x8*)(lds + PG8_SA(b, h) + aoff + m * 2048 + k * 1024); } while (0)
; #define PG8_MMA(ai, bj, At, Bt) do { __builtin_amdgcn_s_setprio(1); _Pragma("unroll") for (int m = 0; m < 4; ++m) _Pragma("unroll") for (int n = 0; n < 2; ++n) _Pragma("unroll") for (int k = 0; k < 2; ++k) \
;         acc[ai][bj][m][n] = __builtin_amdgcn_mfma_f32_16x16x32_bf16(Bt[n][k], At[m][k], acc[ai][bj][m][n], 0, 0, 0); __builtin_amdgcn_s_setprio(0); } while (0)
; #define PG8_WAIT_V(n) asm volatile("s_waitcnt vmcnt(" #n ")" ::: "memory")
; #define PG8_WAIT_L(n) asm volatile("s_waitcnt lgkmcnt(" #n ")" ::: "memory")
; #define PG8_BAR __builtin_amdgcn_s_barrier()
; #define PG8_SCHED __builtin_amdgcn_sched_barrier(0)
; template <class Epi, class Sched, bool ALIGN_EPI = false, bool SP2 = false>
; __device__ __forceinline__ void gemm_phase(PG8_LAS unsigned char* lds, const Gemm g, const Sched& S, const Epi& E) {
;     ...
;         for (int t = 0; t < nt; t += 2) {
;             const bool last = (t == nt - 2);
;             const char* a1 = cA + (size_t)(t + 1) * kstep;
;             const char* a2 = last ? nA : cA + (size_t)(t + 2) * kstep; const char* b2 = last ? nB : cB + (size_t)(t + 2) * kstep;
;             const char* a3 = a2 + kstep; const char* b3 = b2 + kstep;
;     ...
;             PG8_LDA(At, 1, 1); PG8_STAGE(PG8_SB(1, 0), b3, voffB); PG8_STAGE(PG8_SB(1, 1), b3 + hstep, voffB); PG8_STAGE(PG8_SA(1, 0), a3, voffA);
;             PG8_WAIT_V(8); PG8_WAIT_L(0); PG8_BAR; PG8_MMA(1, 0, At, B0); PG8_MMA(1, 1, At, B1); PG8_BAR; PG8_SCHED;
	s_add_i32 s8, s41, s26
	v_lshl_add_u64 v[160:161], v[160:161], 0, s[96:97]
	s_mov_b32 m0, s8
	ds_read_b128 v[202:205], v168 offset:49152
	ds_read_b128 v[206:209], v168 offset:50176
	ds_read_b128 v[210:213], v168 offset:51200
	ds_read_b128 v[228:231], v168 offset:52224
	ds_read_b128 v[232:235], v168 offset:53248
	ds_read_b128 v[236:239], v168 offset:54272
	ds_read_b128 v[240:243], v168 offset:55296
	ds_read_b128 v[244:247], v168 offset:56320
	global_load_lds_dwordx4 v[160:161], off
	s_add_i32 m0, s8, 0x2000
	s_add_u32 s2, s2, 0x40080
	v_lshl_add_u64 v[160:161], v[182:183], 0, s[96:97]
	s_addc_u32 s3, s3, 0
	s_add_i32 s8, s44, s26
	global_load_lds_dwordx4 v[160:161], off
	v_lshl_add_u64 v[160:161], s[2:3], 0, v[140:141]
	s_mov_b32 m0, s8
	s_nop 0
	global_load_lds_dwordx4 v[160:161], off
	v_lshl_add_u64 v[160:161], s[2:3], 0, v[136:137]
	s_add_i32 m0, s8, 0x2000
	s_nop 0
	global_load_lds_dwordx4 v[160:161], off
	v_lshl_add_u64 v[160:161], v[214:215], 0, s[96:97]
	s_mov_b32 m0, s31
	s_nop 0
	global_load_lds_dwordx4 v[160:161], off
	v_lshl_add_u64 v[160:161], v[248:249], 0, s[96:97]
	s_mov_b32 m0, s34
	s_nop 0
	global_load_lds_dwordx4 v[160:161], off
	s_waitcnt vmcnt(8)
	s_waitcnt lgkmcnt(0)
	s_barrier
	s_setprio 1
	s_waitcnt lgkmcnt(0)
	v_mfma_f32_16x16x32_bf16 v[60:63], v[128:131], v[202:205], v[60:63]
	v_mfma_f32_16x16x32_bf16 v[56:59], v[156:159], v[202:205], v[56:59]
	v_mfma_f32_16x16x32_bf16 v[44:47], v[128:131], v[210:213], v[44:47]
	v_mfma_f32_16x16x32_bf16 v[40:43], v[156:159], v[210:213], v[40:43]
	v_mfma_f32_16x16x32_bf16 v[28:31], v[128:131], v[232:235], v[28:31]
	v_mfma_f32_16x16x32_bf16 v[24:27], v[156:159], v[232:235], v[24:27]
	v_mfma_f32_16x16x32_bf16 v[12:15], v[128:131], v[240:243], v[12:15]
	v_mfma_f32_16x16x32_bf16 v[8:11], v[156:159], v[240:243], v[8:11]
	s_setprio 0
	s_setprio 1
	v_mfma_f32_16x16x32_bf16 v[60:63], v[132:135], v[206:209], v[60:63]
	v_mfma_f32_16x16x32_bf16 v[56:59], v[170:173], v[206:209], v[56:59]
	v_mfma_f32_16x16x32_bf16 v[44:47], v[132:135], v[228:231], v[44:47]
	v_mfma_f32_16x16x32_bf16 v[40:43], v[170:173], v[228:231], v[40:43]
	v_mfma_f32_16x16x32_bf16 v[28:31], v[132:135], v[236:239], v[28:31]
	v_mfma_f32_16x16x32_bf16 v[24:27], v[170:173], v[236:239], v[24:27]
	v_mfma_f32_16x16x32_bf16 v[12:15], v[132:135], v[244:247], v[12:15]
	v_mfma_f32_16x16x32_bf16 v[8:11], v[170:173], v[244:247], v[8:11]
	s_setprio 0
	s_setprio 1
	v_mfma_f32_16x16x32_bf16 v[52:55], v[174:177], v[202:205], v[52:55]
	v_mfma_f32_16x16x32_bf16 v[48:51], v[194:197], v[202:205], v[48:51]
	v_mfma_f32_16x16x32_bf16 v[36:39], v[174:177], v[210:213], v[36:39]
	v_mfma_f32_16x16x32_bf16 v[32:35], v[194:197], v[210:213], v[32:35]
	v_mfma_f32_16x16x32_bf16 v[20:23], v[174:177], v[232:235], v[20:23]
	v_mfma_f32_16x16x32_bf16 v[16:19], v[194:197], v[232:235], v[16:19]
	v_mfma_f32_16x16x32_bf16 v[4:7], v[174:177], v[240:243], v[4:7]
	v_mfma_f32_16x16x32_bf16 v[0:3], v[194:197], v[240:243], v[0:3]
	s_setprio 0
	s_setprio 1
	v_mfma_f32_16x16x32_bf16 v[52:55], v[178:181], v[206:209], v[52:55]
	v_mfma_f32_16x16x32_bf16 v[48:51], v[198:201], v[206:209], v[48:51]
	v_mfma_f32_16x16x32_bf16 v[36:39], v[178:181], v[228:231], v[36:39]
	v_mfma_f32_16x16x32_bf16 v[32:35], v[198:201], v[228:231], v[32:35]
	v_mfma_f32_16x16x32_bf16 v[20:23], v[178:181], v[236:239], v[20:23]
	v_mfma_f32_16x16x32_bf16 v[16:19], v[198:201], v[236:239], v[16:19]
	v_mfma_f32_16x16x32_bf16 v[4:7], v[178:181], v[244:247], v[4:7]
	v_mfma_f32_16x16x32_bf16 v[0:3], v[198:201], v[244:247], v[0:3]
	s_setprio 0
	s_barrier
	s_add_i32 s40, s40, 2
	s_add_u32 s0, s0, 0x100
	s_addc_u32 s1, s1, 0
	s_add_u32 s25, s25, 0x100
	s_addc_u32 s39, s39, 0
	s_cmp_gt_u32 s40, 13
	s_cbranch_scc0 .LBB0_509
	s_and_b64 vcc, exec, s[16:17]
	s_cbranch_vccz .LBB0_512
	s_barrier

; #define PG8_STAGE(bufoff, gbase, voff) do { _Pragma("unroll") for (int _i = 0; _i < 2; ++_i) \
;         __builtin_amdgcn_global_load_lds((const unsigned*)((const char*)(gbase) + (voff)[_i]), (PG8_LAS unsigned*)(lds + (bufoff) + ldsw + _i * 8192), 16, 0, 0); } while (0)
; #define PG8_LDA(dst, b, h) do { _Pragma("unroll") for (int m = 0; m < 4; ++m) _Pragma("unroll") for (int k = 0; k < 2; ++k) dst[m][k] = *(const PG8_LAS bf16x8*)(lds + PG8_SA(b, h) + aoff + m * 2048 + k * 1024); } while (0)
; #define PG8_LDB(dst, b, h) do { _Pragma("unroll") for (int n = 0; n < 2; ++n) _Pragma("unroll") for (int k = 0; k < 2; ++k) dst[n][k] = *(const PG8_LAS bf16x8*)(lds + PG8_SB(b, h) + boff + n * 2048 + k * 1024); } while (0)
; #define PG8_MMA(ai, bj, At, Bt) do { __builtin_amdgcn_s_setprio(1); _Pragma("unroll") for (int m = 0; m < 4; ++m) _Pragma("unroll") for (int n = 0; n < 2; ++n) _Pragma("unroll") for (int k = 0; k < 2; ++k) \
;         acc[ai][bj][m][n] = __builtin_amdgcn_mfma_f32_16x16x32_bf16(Bt[n][k], At[m][k], acc[ai][bj][m][n], 0, 0, 0); __builtin_amdgcn_s_setprio(0); } while (0)
; #define PG8_BAR __builtin_amdgcn_s_barrier()
; template <class Epi, class Sched, bool ALIGN_EPI = false, bool SP2 = false>
; __device__ __forceinline__ void gemm_phase(PG8_LAS unsigned char* lds, const Gemm g, const Sched& S, const Epi& E) {
;     ...
;         const bool has_next = S.next(ui + 1, nxt);
;         const char* nA = has_next ? (const char*)g.A + (size_t)nxt.pm * tstep : cA; const char* nB = has_next ? (const char*)g.Bt + (size_t)nxt.pn * tstep : cB;
;         for (int t = 0; t < nt; t += 2) {
;             const bool last = (t == nt - 2);
;             const char* a1 = cA + (size_t)(t + 1) * kstep;
;             const char* a2 = last ? nA : cA + (size_t)(t + 2) * kstep; const char* b2 = last ? nB : cB + (size_t)(t + 2) * kstep;
;             const char* a3 = a2 + kstep; const char* b3 = b2 + kstep;
;             if (last && has_next) S.a_ready(nxt);
;             if constexpr (SP2) {
;             PG8_LDB(B0, 0, 0); PG8_LDB(B1, 0, 1); PG8_SCHED; PG8_LDA(At, 0, 0); PG8_STAGE(PG8_SA(1, 1), a1 + hstep, voffA);
;             PG8_WAIT_V(8); PG8_WAIT_L(0); PG8_BAR; PG8_MMA(0, 0, At, B0); PG8_MMA(0, 1, At, B1); PG8_BAR; PG8_SCHED;
;             PG8_LDA(At, 0, 1); PG8_STAGE(PG8_SB(0, 0), b2, voffB); PG8_STAGE(PG8_SB(0, 1), b2 + hstep, voffB); PG8_STAGE(PG8_SA(0, 0), a2, voffA);
.LBB0_533:
	s_add_u32 s2, s0, 0xfffc0080
	s_addc_u32 s3, s1, -1
	s_add_i32 s39, 0, 0x10000
	s_cmp_eq_u32 s38, 12
	s_cselect_b32 s25, s4, s3
	s_cselect_b32 s24, s5, s2
	s_cselect_b32 s3, s6, s19
	s_cselect_b32 s2, s7, s11
	s_add_i32 s54, 0, 0x14000
	v_add_u32_e32 v140, s39, v155
	v_add_u32_e32 v184, s54, v155
	ds_read_b128 v[128:131], v140
	ds_read_b128 v[132:135], v140 offset:1024
	ds_read_b128 v[136:139], v140 offset:2048
	ds_read_b128 v[140:143], v140 offset:3072
	ds_read_b128 v[170:173], v184
	ds_read_b128 v[174:177], v184 offset:1024
	ds_read_b128 v[180:183], v184 offset:2048
	ds_read_b128 v[194:197], v184 offset:3072
	v_lshl_add_u64 v[214:215], s[0:1], 0, v[166:167]
	s_add_i32 m0, s23, 0xc000
	ds_read_b128 v[198:201], v179
	ds_read_b128 v[202:205], v179 offset:1024
	ds_read_b128 v[206:209], v179 offset:2048
	ds_read_b128 v[210:213], v179 offset:3072
	ds_read_b128 v[228:231], v179 offset:4096
	ds_read_b128 v[232:235], v179 offset:5120
	ds_read_b128 v[236:239], v179 offset:6144
	ds_read_b128 v[240:243], v179 offset:7168
	global_load_lds_dwordx4 v[214:215], off
	v_lshl_add_u64 v[214:215], s[0:1], 0, v[168:169]
	s_add_i32 m0, s23, 0xe000
	s_nop 0
	global_load_lds_dwordx4 v[214:215], off
	s_waitcnt vmcnt(8)
	s_waitcnt lgkmcnt(0)
	s_barrier
	s_setprio 1
	s_waitcnt lgkmcnt(0)
	v_mfma_f32_16x16x32_bf16 v[124:127], v[128:131], v[198:201], v[124:127]
	v_mfma_f32_16x16x32_bf16 v[120:123], v[136:139], v[198:201], v[120:123]
	v_mfma_f32_16x16x32_bf16 v[108:111], v[128:131], v[206:209], v[108:111]
	v_mfma_f32_16x16x32_bf16 v[104:107], v[136:139], v[206:209], v[104:107]
	v_mfma_f32_16x16x32_bf16 v[92:95], v[128:131], v[228:231], v[92:95]
	v_mfma_f32_16x16x32_bf16 v[88:91], v[136:139], v[228:231], v[88:91]
	v_mfma_f32_16x16x32_bf16 v[76:79], v[128:131], v[236:239], v[76:79]
	v_mfma_f32_16x16x32_bf16 v[72:75], v[136:139], v[236:239], v[72:75]
	s_setprio 0
	s_setprio 1
	v_mfma_f32_16x16x32_bf16 v[124:127], v[132:135], v[202:205], v[124:127]
	v_mfma_f32_16x16x32_bf16 v[120:123], v[140:143], v[202:205], v[120:123]
	v_mfma_f32_16x16x32_bf16 v[108:111], v[132:135], v[210:213], v[108:111]
	v_mfma_f32_16x16x32_bf16 v[104:107], v[140:143], v[210:213], v[104:107]
	v_mfma_f32_16x16x32_bf16 v[92:95], v[132:135], v[232:235], v[92:95]
	v_mfma_f32_16x16x32_bf16 v[88:91], v[140:143], v[232:235], v[88:91]
	v_mfma_f32_16x16x32_bf16 v[76:79], v[132:135], v[240:243], v[76:79]
	v_mfma_f32_16x16x32_bf16 v[72:75], v[140:143], v[240:243], v[72:75]
	s_setprio 0
	s_setprio 1
	v_mfma_f32_16x16x32_bf16 v[116:119], v[170:173], v[198:201], v[116:119]
	v_mfma_f32_16x16x32_bf16 v[112:115], v[180:183], v[198:201], v[112:115]
	v_mfma_f32_16x16x32_bf16 v[100:103], v[170:173], v[206:209], v[100:103]
	v_mfma_f32_16x16x32_bf16 v[96:99], v[180:183], v[206:209], v[96:99]
	v_mfma_f32_16x16x32_bf16 v[84:87], v[170:173], v[228:231], v[84:87]
	v_mfma_f32_16x16x32_bf16 v[80:83], v[180:183], v[228:231], v[80:83]
	v_mfma_f32_16x16x32_bf16 v[68:71], v[170:173], v[236:239], v[68:71]
	v_mfma_f32_16x16x32_bf16 v[64:67], v[180:183], v[236:239], v[64:67]
	s_setprio 0
	s_setprio 1
	v_mfma_f32_16x16x32_bf16 v[116:119], v[174:177], v[202:205], v[116:119]
	v_mfma_f32_16x16x32_bf16 v[112:115], v[194:197], v[202:205], v[112:115]
	v_mfma_f32_16x16x32_bf16 v[100:103], v[174:177], v[210:213], v[100:103]
	v_mfma_f32_16x16x32_bf16 v[96:99], v[194:197], v[210:213], v[96:99]
	v_mfma_f32_16x16x32_bf16 v[84:87], v[174:177], v[232:235], v[84:87]
	v_mfma_f32_16x16x32_bf16 v[80:83], v[194:197], v[232:235], v[80:83]
	v_mfma_f32_16x16x32_bf16 v[68:71], v[174:177], v[240:243], v[68:71]
	v_mfma_f32_16x16x32_bf16 v[64:67], v[194:197], v[240:243], v[64:67]
	s_setprio 0
	s_barrier
	s_add_i32 s39, s39, s22
	v_lshl_add_u64 v[214:215], s[2:3], 0, v[148:149]
	s_mov_b32 m0, s39
	ds_read_b128 v[198:201], v179 offset:16384
	ds_read_b128 v[202:205], v179 offset:17408
	ds_read_b128 v[206:209], v179 offset:18432
	ds_read_b128 v[210:213], v179 offset:19456
	ds_read_b128 v[228:231], v179 offset:20480
	ds_read_b128 v[232:235], v179 offset:21504
	ds_read_b128 v[236:239], v179 offset:22528
	ds_read_b128 v[240:243], v179 offset:23552
	global_load_lds_dwordx4 v[214:215], off
	s_add_i32 m0, s39, 0x2000
	s_add_u32 s40, s2, 0x40000
	v_lshl_add_u64 v[224:225], s[2:3], 0, v[144:145]
	s_addc_u32 s41, s3, 0
	s_add_i32 s39, s54, s22
	global_load_lds_dwordx4 v[224:225], off
	v_lshl_add_u64 v[244:245], s[40:41], 0, v[148:149]
	s_mov_b32 m0, s39
	v_lshl_add_u64 v[246:247], s[24:25], 0, v[146:147]
	global_load_lds_dwordx4 v[244:245], off
	v_lshl_add_u64 v[244:245], s[40:41], 0, v[144:145]
	s_add_i32 m0, s39, 0x2000
	s_nop 0
	global_load_lds_dwordx4 v[244:245], off
	v_lshl_add_u64 v[244:245], s[24:25], 0, v[150:151]
	s_mov_b32 m0, s23
	s_nop 0
	global_load_lds_dwordx4 v[244:245], off
	s_mov_b32 m0, s44
	s_nop 0
	global_load_lds_dwordx4 v[246:247], off
	s_waitcnt vmcnt(8)
	s_waitcnt lgkmcnt(0)
	s_barrier
; #define PG8_STAGE(bufoff, gbase, voff) do { _Pragma("unroll") for (int _i = 0; _i < 2; ++_i) \
;         __builtin_amdgcn_global_load_lds((const unsigned*)((const char*)(gbase) + (voff)[_i]), (PG8_LAS unsigned*)(lds + (bufoff) + ldsw + _i * 8192), 16, 0, 0); } while (0)
; #define PG8_LDA(dst, b, h) do { _Pragma("unroll") for (int m = 0; m < 4; ++m) _Pragma("unroll") for (int k = 0; k < 2; ++k) dst[m][k] = *(const PG8_LAS bf16x8*)(lds + PG8_SA(b, h) + aoff + m * 2048 + k * 1024); } while (0)
; #define PG8_LDB(dst, b, h) do { _Pragma("unroll") for (int n = 0; n < 2; ++n) _Pragma("unroll") for (int k = 0; k < 2; ++k) dst[n][k] = *(const PG8_LAS bf16x8*)(lds + PG8_SB(b, h) + boff + n * 2048 + k * 1024); } while (0)
; #define PG8_MMA(ai, bj, At, Bt) do { __builtin_amdgcn_s_setprio(1); _Pragma("unroll") for (int m = 0; m < 4; ++m) _Pragma("unroll") for (int n = 0; n < 2; ++n) _Pragma("unroll") for (int k = 0; k < 2; ++k) \
;         acc[ai][bj][m][n] = __builtin_amdgcn_mfma_f32_16x16x32_bf16(Bt[n][k], At[m][k], acc[ai][bj][m][n], 0, 0, 0); __builtin_amdgcn_s_setprio(0); } while (0)
; #define PG8_WAIT_V(n) asm volatile("s_waitcnt vmcnt(" #n ")" ::: "memory")
; #define PG8_WAIT_L(n) asm volatile("s_waitcnt lgkmcnt(" #n ")" ::: "memory")
; #define PG8_BAR __builtin_amdgcn_s_barrier()
; #define PG8_SCHED __builtin_amdgcn_sched_barrier(0)
; template <class Epi, class Sched, bool ALIGN_EPI = false, bool SP2 = false>
; __device__ __forceinline__ void gemm_phase(PG8_LAS unsigned char* lds, const Gemm g, const Sched& S, const Epi& E) {
;     ...
;             PG8_WAIT_V(8); PG8_WAIT_L(0); PG8_BAR; PG8_MMA(1, 0, At, B0); PG8_MMA(1, 1, At, B1); PG8_BAR; PG8_SCHED;
;             PG8_LDB(B0, 1, 0); PG8_LDB(B1, 1, 1); PG8_SCHED; PG8_LDA(At, 1, 0); PG8_STAGE(PG8_SA(0, 1), a2 + hstep, voffA);
;             PG8_WAIT_V(8); PG8_WAIT_L(0); PG8_BAR; PG8_MMA(0, 0, At, B0); PG8_MMA(0, 1, At, B1); PG8_BAR; PG8_SCHED;
	s_setprio 1
	s_waitcnt lgkmcnt(0)
	v_mfma_f32_16x16x32_bf16 v[60:63], v[128:131], v[198:201], v[60:63]
	v_mfma_f32_16x16x32_bf16 v[56:59], v[136:139], v[198:201], v[56:59]
	v_mfma_f32_16x16x32_bf16 v[44:47], v[128:131], v[206:209], v[44:47]
	v_mfma_f32_16x16x32_bf16 v[40:43], v[136:139], v[206:209], v[40:43]
	v_mfma_f32_16x16x32_bf16 v[28:31], v[128:131], v[228:231], v[28:31]
	v_mfma_f32_16x16x32_bf16 v[24:27], v[136:139], v[228:231], v[24:27]
	v_mfma_f32_16x16x32_bf16 v[12:15], v[128:131], v[236:239], v[12:15]
	v_mfma_f32_16x16x32_bf16 v[8:11], v[136:139], v[236:239], v[8:11]
	s_setprio 0
	s_setprio 1
	v_mfma_f32_16x16x32_bf16 v[60:63], v[132:135], v[202:205], v[60:63]
	v_mfma_f32_16x16x32_bf16 v[56:59], v[140:143], v[202:205], v[56:59]
	v_mfma_f32_16x16x32_bf16 v[44:47], v[132:135], v[210:213], v[44:47]
	v_mfma_f32_16x16x32_bf16 v[40:43], v[140:143], v[210:213], v[40:43]
	v_mfma_f32_16x16x32_bf16 v[28:31], v[132:135], v[232:235], v[28:31]
	v_mfma_f32_16x16x32_bf16 v[24:27], v[140:143], v[232:235], v[24:27]
	v_mfma_f32_16x16x32_bf16 v[12:15], v[132:135], v[240:243], v[12:15]
	v_mfma_f32_16x16x32_bf16 v[8:11], v[140:143], v[240:243], v[8:11]
	s_setprio 0
	s_setprio 1
	v_mfma_f32_16x16x32_bf16 v[52:55], v[170:173], v[198:201], v[52:55]
	v_mfma_f32_16x16x32_bf16 v[48:51], v[180:183], v[198:201], v[48:51]
	v_mfma_f32_16x16x32_bf16 v[36:39], v[170:173], v[206:209], v[36:39]
	v_mfma_f32_16x16x32_bf16 v[32:35], v[180:183], v[206:209], v[32:35]
	v_mfma_f32_16x16x32_bf16 v[20:23], v[170:173], v[228:231], v[20:23]
	v_mfma_f32_16x16x32_bf16 v[16:19], v[180:183], v[228:231], v[16:19]
	v_mfma_f32_16x16x32_bf16 v[4:7], v[170:173], v[236:239], v[4:7]
	v_mfma_f32_16x16x32_bf16 v[0:3], v[180:183], v[236:239], v[0:3]
	s_setprio 0
	s_setprio 1
	v_mfma_f32_16x16x32_bf16 v[52:55], v[174:177], v[202:205], v[52:55]
	v_mfma_f32_16x16x32_bf16 v[48:51], v[194:197], v[202:205], v[48:51]
	v_mfma_f32_16x16x32_bf16 v[36:39], v[174:177], v[210:213], v[36:39]
	v_mfma_f32_16x16x32_bf16 v[32:35], v[194:197], v[210:213], v[32:35]
	v_mfma_f32_16x16x32_bf16 v[20:23], v[174:177], v[232:235], v[20:23]
	v_mfma_f32_16x16x32_bf16 v[16:19], v[194:197], v[232:235], v[16:19]
	v_mfma_f32_16x16x32_bf16 v[4:7], v[174:177], v[240:243], v[4:7]
	v_mfma_f32_16x16x32_bf16 v[0:3], v[194:197], v[240:243], v[0:3]
	s_setprio 0
	s_barrier
	s_add_i32 s39, 0, 0x18000
	s_add_i32 s40, 0, 0x1c000
	v_add_u32_e32 v140, s39, v155
	v_add_u32_e32 v184, s40, v155
	ds_read_b128 v[128:131], v140
	ds_read_b128 v[132:135], v140 offset:1024
	ds_read_b128 v[136:139], v140 offset:2048
	ds_read_b128 v[140:143], v140 offset:3072
	ds_read_b128 v[170:173], v184
	ds_read_b128 v[174:177], v184 offset:1024
	ds_read_b128 v[180:183], v184 offset:2048
	ds_read_b128 v[194:197], v184 offset:3072
	s_add_u32 s24, s24, 0x40000
	s_addc_u32 s25, s25, 0
	s_mov_b32 m0, s45
	v_lshl_add_u64 v[248:249], s[24:25], 0, v[150:151]
	ds_read_b128 v[198:201], v179 offset:32768
	ds_read_b128 v[202:205], v179 offset:33792
	ds_read_b128 v[206:209], v179 offset:34816
	ds_read_b128 v[210:213], v179 offset:35840
	ds_read_b128 v[228:231], v179 offset:36864
	ds_read_b128 v[232:235], v179 offset:37888
	ds_read_b128 v[236:239], v179 offset:38912
	ds_read_b128 v[240:243], v179 offset:39936
	global_load_lds_dwordx4 v[248:249], off
	v_lshl_add_u64 v[248:249], s[24:25], 0, v[146:147]
	s_mov_b32 m0, s46
	s_nop 0
	global_load_lds_dwordx4 v[248:249], off
	s_waitcnt vmcnt(8)
	s_waitcnt lgkmcnt(0)
	s_barrier
	s_setprio 1
	s_waitcnt lgkmcnt(0)
	v_mfma_f32_16x16x32_bf16 v[124:127], v[128:131], v[198:201], v[124:127]
	v_mfma_f32_16x16x32_bf16 v[120:123], v[136:139], v[198:201], v[120:123]
	v_mfma_f32_16x16x32_bf16 v[108:111], v[128:131], v[206:209], v[108:111]
	v_mfma_f32_16x16x32_bf16 v[104:107], v[136:139], v[206:209], v[104:107]
	v_mfma_f32_16x16x32_bf16 v[92:95], v[128:131], v[228:231], v[92:95]
	v_mfma_f32_16x16x32_bf16 v[88:91], v[136:139], v[228:231], v[88:91]
	v_mfma_f32_16x16x32_bf16 v[76:79], v[128:131], v[236:239], v[76:79]
	v_mfma_f32_16x16x32_bf16 v[72:75], v[136:139], v[236:239], v[72:75]
	s_setprio 0
	s_setprio 1
	v_mfma_f32_16x16x32_bf16 v[124:127], v[132:135], v[202:205], v[124:127]
	v_mfma_f32_16x16x32_bf16 v[120:123], v[140:143], v[202:205], v[120:123]
	v_mfma_f32_16x16x32_bf16 v[108:111], v[132:135], v[210:213], v[108:111]
	v_mfma_f32_16x16x32_bf16 v[104:107], v[140:143], v[210:213], v[104:107]
	v_mfma_f32_16x16x32_bf16 v[92:95], v[132:135], v[232:235], v[92:95]
	v_mfma_f32_16x16x32_bf16 v[88:91], v[140:143], v[232:235], v[88:91]
	v_mfma_f32_16x16x32_bf16 v[76:79], v[132:135], v[240:243], v[76:79]
	v_mfma_f32_16x16x32_bf16 v[72:75], v[140:143], v[240:243], v[72:75]
	s_setprio 0
	s_setprio 1
	v_mfma_f32_16x16x32_bf16 v[116:119], v[170:173], v[198:201], v[116:119]
	v_mfma_f32_16x16x32_bf16 v[112:115], v[180:183], v[198:201], v[112:115]
	v_mfma_f32_16x16x32_bf16 v[100:103], v[170:173], v[206:209], v[100:103]
	v_mfma_f32_16x16x32_bf16 v[96:99], v[180:183], v[206:209], v[96:99]
	v_mfma_f32_16x16x32_bf16 v[84:87], v[170:173], v[228:231], v[84:87]
	v_mfma_f32_16x16x32_bf16 v[80:83], v[180:183], v[228:231], v[80:83]
	v_mfma_f32_16x16x32_bf16 v[68:71], v[170:173], v[236:239], v[68:71]
	v_mfma_f32_16x16x32_bf16 v[64:67], v[180:183], v[236:239], v[64:67]
	s_setprio 0
	s_setprio 1
	v_mfma_f32_16x16x32_bf16 v[116:119], v[174:177], v[202:205], v[116:119]
	v_mfma_f32_16x16x32_bf16 v[112:115], v[194:197], v[202:205], v[112:115]
	v_mfma_f32_16x16x32_bf16 v[100:103], v[174:177], v[210:213], v[100:103]
	v_mfma_f32_16x16x32_bf16 v[96:99], v[194:197], v[210:213], v[96:99]
	v_mfma_f32_16x16x32_bf16 v[84:87], v[174:177], v[232:235], v[84:87]
	v_mfma_f32_16x16x32_bf16 v[80:83], v[194:197], v[232:235], v[80:83]
	v_mfma_f32_16x16x32_bf16 v[68:71], v[174:177], v[240:243], v[68:71]
	v_mfma_f32_16x16x32_bf16 v[64:67], v[194:197], v[240:243], v[64:67]
	s_setprio 0
	s_barrier
; #define PG8_STAGE(bufoff, gbase, voff) do { _Pragma("unroll") for (int _i = 0; _i < 2; ++_i) \
;         __builtin_amdgcn_global_load_lds((const unsigned*)((const char*)(gbase) + (voff)[_i]), (PG8_LAS unsigned*)(lds + (bufoff) + ldsw + _i * 8192), 16, 0, 0); } while (0)
; #define PG8_LDA(dst, b, h) do { _Pragma("unroll") for (int m = 0; m < 4; ++m) _Pragma("unroll") for (int k = 0; k < 2; ++k) dst[m][k] = *(const PG8_LAS bf16x8*)(lds + PG8_SA(b, h) + aoff + m * 2048 + k * 1024); } while (0)
; #define PG8_MMA(ai, bj, At, Bt) do { __builtin_amdgcn_s_setprio(1); _Pragma("unroll") for (int m = 0; m < 4; ++m) _Pragma("unroll") for (int n = 0; n < 2; ++n) _Pragma("unroll") for (int k = 0; k < 2; ++k) \
;         acc[ai][bj][m][n] = __builtin_amdgcn_mfma_f32_16x16x32_bf16(Bt[n][k], At[m][k], acc[ai][bj][m][n], 0, 0, 0); __builtin_amdgcn_s_setprio(0); } while (0)
; #define PG8_WAIT_V(n) asm volatile("s_waitcnt vmcnt(" #n ")" ::: "memory")
; #define PG8_WAIT_L(n) asm volatile("s_waitcnt lgkmcnt(" #n ")" ::: "memory")
; #define PG8_BAR __builtin_amdgcn_s_barrier()
; #define PG8_SCHED __builtin_amdgcn_sched_barrier(0)
; template <class Epi, class Sched, bool ALIGN_EPI = false, bool SP2 = false>
; __device__ __forceinline__ void gemm_phase(PG8_LAS unsigned char* lds, const Gemm g, const Sched& S, const Epi& E) {
;     ...
;         for (int t = 0; t < nt; t += 2) {
;             const bool last = (t == nt - 2);
;             const char* a1 = cA + (size_t)(t + 1) * kstep;
;             const char* a2 = last ? nA : cA + (size_t)(t + 2) * kstep; const char* b2 = last ? nB : cB + (size_t)(t + 2) * kstep;
;             const char* a3 = a2 + kstep; const char* b3 = b2 + kstep;
;     ...
;             PG8_LDA(At, 1, 1); PG8_STAGE(PG8_SB(1, 0), b3, voffB); PG8_STAGE(PG8_SB(1, 1), b3 + hstep, voffB); PG8_STAGE(PG8_SA(1, 0), a3, voffA);
;             PG8_WAIT_V(8); PG8_WAIT_L(0); PG8_BAR; PG8_MMA(1, 0, At, B0); PG8_MMA(1, 1, At, B1); PG8_BAR; PG8_SCHED;
	s_add_i32 s24, s39, s22
	v_lshl_add_u64 v[214:215], v[214:215], 0, s[96:97]
	s_mov_b32 m0, s24
	ds_read_b128 v[198:201], v179 offset:49152
	ds_read_b128 v[202:205], v179 offset:50176
	ds_read_b128 v[206:209], v179 offset:51200
	ds_read_b128 v[210:213], v179 offset:52224
	ds_read_b128 v[228:231], v179 offset:53248
	ds_read_b128 v[232:235], v179 offset:54272
	ds_read_b128 v[236:239], v179 offset:55296
	ds_read_b128 v[240:243], v179 offset:56320
	global_load_lds_dwordx4 v[214:215], off
	s_add_i32 m0, s24, 0x2000
	s_add_u32 s2, s2, 0x40080
	v_lshl_add_u64 v[214:215], v[224:225], 0, s[96:97]
	s_addc_u32 s3, s3, 0
	s_add_i32 s24, s40, s22
	global_load_lds_dwordx4 v[214:215], off
	v_lshl_add_u64 v[214:215], s[2:3], 0, v[148:149]
	s_mov_b32 m0, s24
	s_nop 0
	global_load_lds_dwordx4 v[214:215], off
	v_lshl_add_u64 v[214:215], s[2:3], 0, v[144:145]
	s_add_i32 m0, s24, 0x2000
	s_nop 0
	global_load_lds_dwordx4 v[214:215], off
	v_lshl_add_u64 v[214:215], v[244:245], 0, s[96:97]
	s_mov_b32 m0, s47
	s_nop 0
	global_load_lds_dwordx4 v[214:215], off
	v_lshl_add_u64 v[214:215], v[246:247], 0, s[96:97]
	s_mov_b32 m0, s48
	s_nop 0
	global_load_lds_dwordx4 v[214:215], off
	s_waitcnt vmcnt(8)
	s_waitcnt lgkmcnt(0)
	s_barrier
	s_setprio 1
	s_waitcnt lgkmcnt(0)
	v_mfma_f32_16x16x32_bf16 v[60:63], v[128:131], v[198:201], v[60:63]
	v_mfma_f32_16x16x32_bf16 v[56:59], v[136:139], v[198:201], v[56:59]
	v_mfma_f32_16x16x32_bf16 v[44:47], v[128:131], v[206:209], v[44:47]
	v_mfma_f32_16x16x32_bf16 v[40:43], v[136:139], v[206:209], v[40:43]
	v_mfma_f32_16x16x32_bf16 v[28:31], v[128:131], v[228:231], v[28:31]
	v_mfma_f32_16x16x32_bf16 v[24:27], v[136:139], v[228:231], v[24:27]
	v_mfma_f32_16x16x32_bf16 v[12:15], v[128:131], v[236:239], v[12:15]
	v_mfma_f32_16x16x32_bf16 v[8:11], v[136:139], v[236:239], v[8:11]
	s_setprio 0
	s_setprio 1
	v_mfma_f32_16x16x32_bf16 v[60:63], v[132:135], v[202:205], v[60:63]
	v_mfma_f32_16x16x32_bf16 v[56:59], v[140:143], v[202:205], v[56:59]
	v_mfma_f32_16x16x32_bf16 v[44:47], v[132:135], v[210:213], v[44:47]
	v_mfma_f32_16x16x32_bf16 v[40:43], v[140:143], v[210:213], v[40:43]
	v_mfma_f32_16x16x32_bf16 v[28:31], v[132:135], v[232:235], v[28:31]
	v_mfma_f32_16x16x32_bf16 v[24:27], v[140:143], v[232:235], v[24:27]
	v_mfma_f32_16x16x32_bf16 v[12:15], v[132:135], v[240:243], v[12:15]
	v_mfma_f32_16x16x32_bf16 v[8:11], v[140:143], v[240:243], v[8:11]
	s_setprio 0
	s_setprio 1
	v_mfma_f32_16x16x32_bf16 v[52:55], v[170:173], v[198:201], v[52:55]
	v_mfma_f32_16x16x32_bf16 v[48:51], v[180:183], v[198:201], v[48:51]
	v_mfma_f32_16x16x32_bf16 v[36:39], v[170:173], v[206:209], v[36:39]
	v_mfma_f32_16x16x32_bf16 v[32:35], v[180:183], v[206:209], v[32:35]
	v_mfma_f32_16x16x32_bf16 v[20:23], v[170:173], v[228:231], v[20:23]
	v_mfma_f32_16x16x32_bf16 v[16:19], v[180:183], v[228:231], v[16:19]
	v_mfma_f32_16x16x32_bf16 v[4:7], v[170:173], v[236:239], v[4:7]
	v_mfma_f32_16x16x32_bf16 v[0:3], v[180:183], v[236:239], v[0:3]
	s_setprio 0
	s_setprio 1
	v_mfma_f32_16x16x32_bf16 v[52:55], v[174:177], v[202:205], v[52:55]
	v_mfma_f32_16x16x32_bf16 v[48:51], v[194:197], v[202:205], v[48:51]
	v_mfma_f32_16x16x32_bf16 v[36:39], v[174:177], v[210:213], v[36:39]
	v_mfma_f32_16x16x32_bf16 v[32:35], v[194:197], v[210:213], v[32:35]
	v_mfma_f32_16x16x32_bf16 v[20:23], v[174:177], v[232:235], v[20:23]
	v_mfma_f32_16x16x32_bf16 v[16:19], v[194:197], v[232:235], v[16:19]
	v_mfma_f32_16x16x32_bf16 v[4:7], v[174:177], v[240:243], v[4:7]
	v_mfma_f32_16x16x32_bf16 v[0:3], v[194:197], v[240:243], v[0:3]
	s_setprio 0
	s_barrier
	s_add_i32 s38, s38, 2
	s_add_u32 s0, s0, 0x100
	s_addc_u32 s1, s1, 0
	s_add_u32 s11, s11, 0x100
	s_addc_u32 s19, s19, 0
	s_cmp_gt_u32 s38, 13
	s_cbranch_scc0 .LBB0_533
	s_and_b64 vcc, exec, s[14:15]
	s_cbranch_vccz .LBB0_536
	s_barrier
